# GEMM K-loops: prefetch loads spread 1 per MFMA group across all 4 slices; every LDS write group now waits vmcnt 19..16
# speedup vs baseline: 1.1360x; 1.0006x over previous
; #define GLOAD(RA, RB, kt) { _Pragma("unroll") for (int i = 0; i < 8; ++i) { const int ia = (tail && i >= 4) ? i - 4 : i; \
;     RA[i] = *(const u32x4*)(abase + ((size_t)(32 * ia) * lda + (kt) * 64) * 2 + aoff); RB[i] = *(const u32x4*)(bbase + ((size_t)(32 * i) * K + (kt) * 64) * 2 + boff); } }
; #define LWRITE(RA, RB, buf) { char* as_ = lds + (buf) * 2 * G_TILE; char* bs_ = as_ + G_TILE; _Pragma("unroll") for (int i = 0; i < 8; ++i) { *(u32x4*)(as_ + (lrow + 32 * i) * GS_B + lch * 16) = RA[i]; *(u32x4*)(bs_ + (lrow + 32 * i) * GS_B + lch * 16) = RB[i]; } }
; template <int EPI>
; DEV void gemm_tile(CParams& p, int layer, const bf16_t* __restrict__ A, int lda, const bf16_t* __restrict__ Bt, int K, int m0, int n0, int nt, char* lds, const int swave) {
;     ...
;   const char* asr = lds + (wm * 128 + lr) * GS_B + hh * 16;
;   const char* bsr = lds + G_TILE + (wn * 128 + lr) * GS_B + hh * 16;
;   char* wsw = lds + lrow * GS_B + lch * 16;
;     ...
;   GLOAD(ra0, rb0, 0); GLOAD(ra1, rb1, 1); LWRITE(ra0, rb0, 0); __syncthreads();
; #pragma unroll 1
;   for (int kt = 0; kt < nk; kt += 2) {
;     if (kt + 2 < nk) GLOAD(ra0, rb0, kt + 2);
;     COMPUTE(0, ra1, rb1, 1, true);
;     __syncthreads();
.LBB0_101:
	s_cmp_eq_u32 s36, 0
	s_cbranch_scc0 .Lzi_i1
	ds_read_b128 v[188:191], v49
	ds_read_b128 v[192:195], v49 offset:4608
	ds_read_b128 v[196:199], v49 offset:9216
	ds_read_b128 v[200:203], v49 offset:13824
	ds_read_b128 v[184:187], v48
	ds_read_b128 v[204:207], v48 offset:4608
	s_waitcnt lgkmcnt(1)
	v_mfma_f32_32x32x16_bf16 a[192:207], v[184:187], v[188:191], 0
	v_mfma_f32_32x32x16_bf16 a[128:143], v[184:187], v[192:195], 0
	v_mfma_f32_32x32x16_bf16 a[64:79], v[184:187], v[196:199], 0
	v_mfma_f32_32x32x16_bf16 a[0:15], v[184:187], v[200:203], 0
	ds_read_b128 v[184:187], v48 offset:9216
	ds_read_b128 v[208:211], v49 offset:32
	ds_read_b128 v[212:215], v49 offset:4640
	v_lshl_add_u64 v[50:51], v[0:1], 0, s[34:35]
	global_load_dwordx4 v[52:55], v[50:51], off
	s_waitcnt lgkmcnt(3)
	v_mfma_f32_32x32x16_bf16 a[208:223], v[204:207], v[188:191], 0
	v_mfma_f32_32x32x16_bf16 a[144:159], v[204:207], v[192:195], 0
	v_mfma_f32_32x32x16_bf16 a[80:95], v[204:207], v[196:199], 0
	v_mfma_f32_32x32x16_bf16 a[16:31], v[204:207], v[200:203], 0
	ds_read_b128 v[204:207], v48 offset:13824
	ds_read_b128 v[216:219], v49 offset:9248
	ds_read_b128 v[220:223], v49 offset:13856
	v_lshl_add_u64 v[50:51], v[2:3], 0, s[34:35]
	s_or_b32 s2, s34, 0x10000
	s_mov_b32 s3, s35
	global_load_dwordx4 v[56:59], v[50:51], off
	s_waitcnt lgkmcnt(5)
	v_mfma_f32_32x32x16_bf16 a[224:239], v[184:187], v[188:191], 0
	v_mfma_f32_32x32x16_bf16 a[160:175], v[184:187], v[192:195], 0
	v_mfma_f32_32x32x16_bf16 a[96:111], v[184:187], v[196:199], 0
	v_mfma_f32_32x32x16_bf16 a[32:47], v[184:187], v[200:203], 0
	ds_read_b128 v[184:187], v48 offset:32
	v_lshl_add_u64 v[50:51], v[0:1], 0, s[2:3]
	global_load_dwordx4 v[60:63], v[50:51], off
	s_waitcnt lgkmcnt(3)
	v_mfma_f32_32x32x16_bf16 a[240:255], v[204:207], v[188:191], 0
	v_mfma_f32_32x32x16_bf16 a[176:191], v[204:207], v[192:195], 0
	v_mfma_f32_32x32x16_bf16 a[112:127], v[204:207], v[196:199], 0
	v_mfma_f32_32x32x16_bf16 a[48:63], v[204:207], v[200:203], 0
	ds_read_b128 v[204:207], v48 offset:4640
	v_lshl_add_u64 v[50:51], v[2:3], 0, s[2:3]
	s_or_b32 s2, s34, 0x20000
	global_load_dwordx4 v[68:71], v[50:51], off
	s_waitcnt vmcnt(19)
	ds_write_b128 v31, v[100:103]
	s_waitcnt vmcnt(18)
	ds_write_b128 v32, v[104:107]
	s_waitcnt vmcnt(17)
	ds_write_b128 v41, v[112:115]
	s_waitcnt vmcnt(16)
	ds_write_b128 v42, v[116:119]
	s_waitcnt lgkmcnt(5)
	v_mfma_f32_32x32x16_bf16 a[192:207], v[184:187], v[208:211], a[192:207]
	v_mfma_f32_32x32x16_bf16 a[128:143], v[184:187], v[212:215], a[128:143]
	v_mfma_f32_32x32x16_bf16 a[64:79], v[184:187], v[216:219], a[64:79]
	v_mfma_f32_32x32x16_bf16 a[0:15], v[184:187], v[220:223], a[0:15]
	ds_read_b128 v[184:187], v48 offset:9248
	ds_read_b128 v[188:191], v49 offset:64
	ds_read_b128 v[192:195], v49 offset:4672
	v_lshl_add_u64 v[50:51], v[0:1], 0, s[2:3]
	global_load_dwordx4 v[72:75], v[50:51], off
	s_waitcnt lgkmcnt(7)
	v_mfma_f32_32x32x16_bf16 a[208:223], v[204:207], v[208:211], a[208:223]
	v_mfma_f32_32x32x16_bf16 a[144:159], v[204:207], v[212:215], a[144:159]
	v_mfma_f32_32x32x16_bf16 a[80:95], v[204:207], v[216:219], a[80:95]
	v_mfma_f32_32x32x16_bf16 a[16:31], v[204:207], v[220:223], a[16:31]
	ds_read_b128 v[204:207], v48 offset:13856
	ds_read_b128 v[196:199], v49 offset:9280
	ds_read_b128 v[200:203], v49 offset:13888
	v_lshl_add_u64 v[50:51], v[2:3], 0, s[2:3]
	s_or_b32 s2, s34, 0x30000
	global_load_dwordx4 v[76:79], v[50:51], off
	s_waitcnt lgkmcnt(5)
	v_mfma_f32_32x32x16_bf16 a[224:239], v[184:187], v[208:211], a[224:239]
	v_mfma_f32_32x32x16_bf16 a[160:175], v[184:187], v[212:215], a[160:175]
	v_mfma_f32_32x32x16_bf16 a[96:111], v[184:187], v[216:219], a[96:111]
	v_mfma_f32_32x32x16_bf16 a[32:47], v[184:187], v[220:223], a[32:47]
	ds_read_b128 v[184:187], v48 offset:64
	v_lshl_add_u64 v[50:51], v[0:1], 0, s[2:3]
	global_load_dwordx4 v[80:83], v[50:51], off
	s_waitcnt lgkmcnt(3)
	v_mfma_f32_32x32x16_bf16 a[240:255], v[204:207], v[208:211], a[240:255]
	v_mfma_f32_32x32x16_bf16 a[176:191], v[204:207], v[212:215], a[176:191]
	v_mfma_f32_32x32x16_bf16 a[112:127], v[204:207], v[216:219], a[112:127]
	v_mfma_f32_32x32x16_bf16 a[48:63], v[204:207], v[220:223], a[48:63]
	ds_read_b128 v[204:207], v48 offset:4672
	v_lshl_add_u64 v[50:51], v[2:3], 0, s[2:3]
	s_or_b32 s2, s34, 0x40000
	global_load_dwordx4 v[84:87], v[50:51], off
	s_waitcnt vmcnt(19)
	ds_write_b128 v37, v[120:123]
	s_waitcnt vmcnt(18)
	ds_write_b128 v38, v[128:131]
	s_waitcnt vmcnt(17)
	ds_write_b128 v39, v[132:135]
	s_waitcnt vmcnt(16)
	ds_write_b128 v40, v[136:139]
	s_waitcnt lgkmcnt(5)
	v_mfma_f32_32x32x16_bf16 a[192:207], v[184:187], v[188:191], a[192:207]
	v_mfma_f32_32x32x16_bf16 a[128:143], v[184:187], v[192:195], a[128:143]
	v_mfma_f32_32x32x16_bf16 a[64:79], v[184:187], v[196:199], a[64:79]
	v_mfma_f32_32x32x16_bf16 a[0:15], v[184:187], v[200:203], a[0:15]
	ds_read_b128 v[184:187], v48 offset:9280
	ds_read_b128 v[208:211], v49 offset:96
	ds_read_b128 v[212:215], v49 offset:4704
	v_lshl_add_u64 v[50:51], v[0:1], 0, s[2:3]
	global_load_dwordx4 v[88:91], v[50:51], off
	s_waitcnt lgkmcnt(7)
	v_mfma_f32_32x32x16_bf16 a[208:223], v[204:207], v[188:191], a[208:223]
	v_mfma_f32_32x32x16_bf16 a[144:159], v[204:207], v[192:195], a[144:159]
	v_mfma_f32_32x32x16_bf16 a[80:95], v[204:207], v[196:199], a[80:95]
	v_mfma_f32_32x32x16_bf16 a[16:31], v[204:207], v[200:203], a[16:31]
	ds_read_b128 v[204:207], v48 offset:13888
	ds_read_b128 v[216:219], v49 offset:9312
	ds_read_b128 v[220:223], v49 offset:13920
	v_lshl_add_u64 v[50:51], v[2:3], 0, s[2:3]
	s_or_b32 s2, s34, 0x50000
	global_load_dwordx4 v[92:95], v[50:51], off
	s_waitcnt lgkmcnt(5)
; #define GLOAD(RA, RB, kt) { _Pragma("unroll") for (int i = 0; i < 8; ++i) { const int ia = (tail && i >= 4) ? i - 4 : i; \
;     RA[i] = *(const u32x4*)(abase + ((size_t)(32 * ia) * lda + (kt) * 64) * 2 + aoff); RB[i] = *(const u32x4*)(bbase + ((size_t)(32 * i) * K + (kt) * 64) * 2 + boff); } }
; #define LWRITE(RA, RB, buf) { char* as_ = lds + (buf) * 2 * G_TILE; char* bs_ = as_ + G_TILE; _Pragma("unroll") for (int i = 0; i < 8; ++i) { *(u32x4*)(as_ + (lrow + 32 * i) * GS_B + lch * 16) = RA[i]; *(u32x4*)(bs_ + (lrow + 32 * i) * GS_B + lch * 16) = RB[i]; } }
; template <int EPI>
; DEV void gemm_tile(CParams& p, int layer, const bf16_t* __restrict__ A, int lda, const bf16_t* __restrict__ Bt, int K, int m0, int n0, int nt, char* lds, const int swave) {
;     ...
;   const char* asr = lds + (wm * 128 + lr) * GS_B + hh * 16;
;   const char* bsr = lds + G_TILE + (wn * 128 + lr) * GS_B + hh * 16;
;   char* wsw = lds + lrow * GS_B + lch * 16;
;     ...
;   GLOAD(ra0, rb0, 0); GLOAD(ra1, rb1, 1); LWRITE(ra0, rb0, 0); __syncthreads();
; #pragma unroll 1
;   for (int kt = 0; kt < nk; kt += 2) {
;     if (kt + 2 < nk) GLOAD(ra0, rb0, kt + 2);
;     COMPUTE(0, ra1, rb1, 1, true);
;     __syncthreads();
	v_mfma_f32_32x32x16_bf16 a[224:239], v[184:187], v[188:191], a[224:239]
	v_mfma_f32_32x32x16_bf16 a[160:175], v[184:187], v[192:195], a[160:175]
	v_mfma_f32_32x32x16_bf16 a[96:111], v[184:187], v[196:199], a[96:111]
	v_mfma_f32_32x32x16_bf16 a[32:47], v[184:187], v[200:203], a[32:47]
	ds_read_b128 v[184:187], v48 offset:96
	v_lshl_add_u64 v[50:51], v[0:1], 0, s[2:3]
	global_load_dwordx4 v[96:99], v[50:51], off
	s_waitcnt lgkmcnt(3)
	v_mfma_f32_32x32x16_bf16 a[240:255], v[204:207], v[188:191], a[240:255]
	v_mfma_f32_32x32x16_bf16 a[176:191], v[204:207], v[192:195], a[176:191]
	v_mfma_f32_32x32x16_bf16 a[112:127], v[204:207], v[196:199], a[112:127]
	v_mfma_f32_32x32x16_bf16 a[48:63], v[204:207], v[200:203], a[48:63]
	ds_read_b128 v[204:207], v48 offset:4704
	v_lshl_add_u64 v[50:51], v[2:3], 0, s[2:3]
	s_or_b32 s2, s34, 0x60000
	global_load_dwordx4 v[108:111], v[50:51], off
	s_waitcnt vmcnt(19)
	ds_write_b128 v33, v[140:143]
	s_waitcnt vmcnt(18)
	ds_write_b128 v34, v[148:151]
	s_waitcnt vmcnt(17)
	ds_write_b128 v35, v[152:155]
	s_waitcnt vmcnt(16)
	ds_write_b128 v36, v[156:159]
	s_waitcnt lgkmcnt(5)
	v_mfma_f32_32x32x16_bf16 a[192:207], v[184:187], v[208:211], a[192:207]
	v_mfma_f32_32x32x16_bf16 a[128:143], v[184:187], v[212:215], a[128:143]
	v_mfma_f32_32x32x16_bf16 a[64:79], v[184:187], v[216:219], a[64:79]
	v_mfma_f32_32x32x16_bf16 a[0:15], v[184:187], v[220:223], a[0:15]
	ds_read_b128 v[184:187], v48 offset:9312
	v_lshl_add_u64 v[50:51], v[0:1], 0, s[2:3]
	global_load_dwordx4 v[124:127], v[50:51], off
	s_waitcnt lgkmcnt(5)
	v_mfma_f32_32x32x16_bf16 a[208:223], v[204:207], v[208:211], a[208:223]
	v_mfma_f32_32x32x16_bf16 a[144:159], v[204:207], v[212:215], a[144:159]
	v_mfma_f32_32x32x16_bf16 a[80:95], v[204:207], v[216:219], a[80:95]
	v_mfma_f32_32x32x16_bf16 a[16:31], v[204:207], v[220:223], a[16:31]
	ds_read_b128 v[204:207], v48 offset:13920
	v_lshl_add_u64 v[50:51], v[2:3], 0, s[2:3]
	s_or_b32 s34, s34, 0x70000
	global_load_dwordx4 v[144:147], v[50:51], off
	s_waitcnt lgkmcnt(1)
	v_mfma_f32_32x32x16_bf16 a[224:239], v[184:187], v[208:211], a[224:239]
	v_mfma_f32_32x32x16_bf16 a[160:175], v[184:187], v[212:215], a[160:175]
	v_mfma_f32_32x32x16_bf16 a[96:111], v[184:187], v[216:219], a[96:111]
	v_mfma_f32_32x32x16_bf16 a[32:47], v[184:187], v[220:223], a[32:47]
	v_lshl_add_u64 v[50:51], v[0:1], 0, s[34:35]
	global_load_dwordx4 v[160:163], v[50:51], off
	s_waitcnt lgkmcnt(0)
	v_mfma_f32_32x32x16_bf16 a[240:255], v[204:207], v[208:211], a[240:255]
	v_mfma_f32_32x32x16_bf16 a[176:191], v[204:207], v[212:215], a[176:191]
	v_mfma_f32_32x32x16_bf16 a[112:127], v[204:207], v[216:219], a[112:127]
	v_mfma_f32_32x32x16_bf16 a[48:63], v[204:207], v[220:223], a[48:63]
	v_lshl_add_u64 v[50:51], v[2:3], 0, s[34:35]
	global_load_dwordx4 v[180:183], v[50:51], off
	s_waitcnt vmcnt(19)
	ds_write_b128 v43, v[164:167]
	s_waitcnt vmcnt(18)
	ds_write_b128 v44, v[168:171]
	s_waitcnt vmcnt(17)
	ds_write_b128 v45, v[172:175]
	s_waitcnt vmcnt(16)
	ds_write_b128 v46, v[176:179]
	s_branch .LBB0_117
.Lzi_i1:
	ds_read_b128 v[188:191], v49
	ds_read_b128 v[192:195], v49 offset:4608
	ds_read_b128 v[196:199], v49 offset:9216
	ds_read_b128 v[200:203], v49 offset:13824
	ds_read_b128 v[184:187], v48
	ds_read_b128 v[204:207], v48 offset:4608
	s_waitcnt lgkmcnt(1)
	v_mfma_f32_32x32x16_bf16 a[192:207], v[184:187], v[188:191], a[192:207]
	v_mfma_f32_32x32x16_bf16 a[128:143], v[184:187], v[192:195], a[128:143]
	v_mfma_f32_32x32x16_bf16 a[64:79], v[184:187], v[196:199], a[64:79]
	v_mfma_f32_32x32x16_bf16 a[0:15], v[184:187], v[200:203], a[0:15]
	ds_read_b128 v[184:187], v48 offset:9216
	ds_read_b128 v[208:211], v49 offset:32
	ds_read_b128 v[212:215], v49 offset:4640
	v_lshl_add_u64 v[50:51], v[0:1], 0, s[34:35]
	global_load_dwordx4 v[52:55], v[50:51], off
	s_waitcnt lgkmcnt(3)
	v_mfma_f32_32x32x16_bf16 a[208:223], v[204:207], v[188:191], a[208:223]
	v_mfma_f32_32x32x16_bf16 a[144:159], v[204:207], v[192:195], a[144:159]
	v_mfma_f32_32x32x16_bf16 a[80:95], v[204:207], v[196:199], a[80:95]
	v_mfma_f32_32x32x16_bf16 a[16:31], v[204:207], v[200:203], a[16:31]
	ds_read_b128 v[204:207], v48 offset:13824
	ds_read_b128 v[216:219], v49 offset:9248
	ds_read_b128 v[220:223], v49 offset:13856
	v_lshl_add_u64 v[50:51], v[2:3], 0, s[34:35]
	s_or_b32 s2, s34, 0x10000
	s_mov_b32 s3, s35
	global_load_dwordx4 v[56:59], v[50:51], off
	s_waitcnt lgkmcnt(5)
	v_mfma_f32_32x32x16_bf16 a[224:239], v[184:187], v[188:191], a[224:239]
	v_mfma_f32_32x32x16_bf16 a[160:175], v[184:187], v[192:195], a[160:175]
	v_mfma_f32_32x32x16_bf16 a[96:111], v[184:187], v[196:199], a[96:111]
	v_mfma_f32_32x32x16_bf16 a[32:47], v[184:187], v[200:203], a[32:47]
	ds_read_b128 v[184:187], v48 offset:32
	v_lshl_add_u64 v[50:51], v[0:1], 0, s[2:3]
	global_load_dwordx4 v[60:63], v[50:51], off
	s_waitcnt lgkmcnt(3)
	v_mfma_f32_32x32x16_bf16 a[240:255], v[204:207], v[188:191], a[240:255]
	v_mfma_f32_32x32x16_bf16 a[176:191], v[204:207], v[192:195], a[176:191]
	v_mfma_f32_32x32x16_bf16 a[112:127], v[204:207], v[196:199], a[112:127]
	v_mfma_f32_32x32x16_bf16 a[48:63], v[204:207], v[200:203], a[48:63]
	ds_read_b128 v[204:207], v48 offset:4640
	v_lshl_add_u64 v[50:51], v[2:3], 0, s[2:3]
	s_or_b32 s2, s34, 0x20000
	global_load_dwordx4 v[68:71], v[50:51], off
	s_waitcnt vmcnt(19)
	ds_write_b128 v31, v[100:103]
	s_waitcnt vmcnt(18)
	ds_write_b128 v32, v[104:107]
	s_waitcnt vmcnt(17)
	ds_write_b128 v41, v[112:115]
	s_waitcnt vmcnt(16)
	ds_write_b128 v42, v[116:119]
	s_waitcnt lgkmcnt(5)
; #define GLOAD(RA, RB, kt) { _Pragma("unroll") for (int i = 0; i < 8; ++i) { const int ia = (tail && i >= 4) ? i - 4 : i; \
;     RA[i] = *(const u32x4*)(abase + ((size_t)(32 * ia) * lda + (kt) * 64) * 2 + aoff); RB[i] = *(const u32x4*)(bbase + ((size_t)(32 * i) * K + (kt) * 64) * 2 + boff); } }
; #define LWRITE(RA, RB, buf) { char* as_ = lds + (buf) * 2 * G_TILE; char* bs_ = as_ + G_TILE; _Pragma("unroll") for (int i = 0; i < 8; ++i) { *(u32x4*)(as_ + (lrow + 32 * i) * GS_B + lch * 16) = RA[i]; *(u32x4*)(bs_ + (lrow + 32 * i) * GS_B + lch * 16) = RB[i]; } }
; template <int EPI>
; DEV void gemm_tile(CParams& p, int layer, const bf16_t* __restrict__ A, int lda, const bf16_t* __restrict__ Bt, int K, int m0, int n0, int nt, char* lds, const int swave) {
;     ...
;   GLOAD(ra0, rb0, 0); GLOAD(ra1, rb1, 1); LWRITE(ra0, rb0, 0); __syncthreads();
; #pragma unroll 1
;   for (int kt = 0; kt < nk; kt += 2) {
;     if (kt + 2 < nk) GLOAD(ra0, rb0, kt + 2);
;     COMPUTE(0, ra1, rb1, 1, true);
;     __syncthreads();
	v_mfma_f32_32x32x16_bf16 a[192:207], v[184:187], v[208:211], a[192:207]
	v_mfma_f32_32x32x16_bf16 a[128:143], v[184:187], v[212:215], a[128:143]
	v_mfma_f32_32x32x16_bf16 a[64:79], v[184:187], v[216:219], a[64:79]
	v_mfma_f32_32x32x16_bf16 a[0:15], v[184:187], v[220:223], a[0:15]
	ds_read_b128 v[184:187], v48 offset:9248
	ds_read_b128 v[188:191], v49 offset:64
	ds_read_b128 v[192:195], v49 offset:4672
	v_lshl_add_u64 v[50:51], v[0:1], 0, s[2:3]
	global_load_dwordx4 v[72:75], v[50:51], off
	s_waitcnt lgkmcnt(7)
	v_mfma_f32_32x32x16_bf16 a[208:223], v[204:207], v[208:211], a[208:223]
	v_mfma_f32_32x32x16_bf16 a[144:159], v[204:207], v[212:215], a[144:159]
	v_mfma_f32_32x32x16_bf16 a[80:95], v[204:207], v[216:219], a[80:95]
	v_mfma_f32_32x32x16_bf16 a[16:31], v[204:207], v[220:223], a[16:31]
	ds_read_b128 v[204:207], v48 offset:13856
	ds_read_b128 v[196:199], v49 offset:9280
	ds_read_b128 v[200:203], v49 offset:13888
	v_lshl_add_u64 v[50:51], v[2:3], 0, s[2:3]
	s_or_b32 s2, s34, 0x30000
	global_load_dwordx4 v[76:79], v[50:51], off
	s_waitcnt lgkmcnt(5)
	v_mfma_f32_32x32x16_bf16 a[224:239], v[184:187], v[208:211], a[224:239]
	v_mfma_f32_32x32x16_bf16 a[160:175], v[184:187], v[212:215], a[160:175]
	v_mfma_f32_32x32x16_bf16 a[96:111], v[184:187], v[216:219], a[96:111]
	v_mfma_f32_32x32x16_bf16 a[32:47], v[184:187], v[220:223], a[32:47]
	ds_read_b128 v[184:187], v48 offset:64
	v_lshl_add_u64 v[50:51], v[0:1], 0, s[2:3]
	global_load_dwordx4 v[80:83], v[50:51], off
	s_waitcnt lgkmcnt(3)
	v_mfma_f32_32x32x16_bf16 a[240:255], v[204:207], v[208:211], a[240:255]
	v_mfma_f32_32x32x16_bf16 a[176:191], v[204:207], v[212:215], a[176:191]
	v_mfma_f32_32x32x16_bf16 a[112:127], v[204:207], v[216:219], a[112:127]
	v_mfma_f32_32x32x16_bf16 a[48:63], v[204:207], v[220:223], a[48:63]
	ds_read_b128 v[204:207], v48 offset:4672
	v_lshl_add_u64 v[50:51], v[2:3], 0, s[2:3]
	s_or_b32 s2, s34, 0x40000
	global_load_dwordx4 v[84:87], v[50:51], off
	s_waitcnt vmcnt(19)
	ds_write_b128 v37, v[120:123]
	s_waitcnt vmcnt(18)
	ds_write_b128 v38, v[128:131]
	s_waitcnt vmcnt(17)
	ds_write_b128 v39, v[132:135]
	s_waitcnt vmcnt(16)
	ds_write_b128 v40, v[136:139]
	s_waitcnt lgkmcnt(5)
	v_mfma_f32_32x32x16_bf16 a[192:207], v[184:187], v[188:191], a[192:207]
	v_mfma_f32_32x32x16_bf16 a[128:143], v[184:187], v[192:195], a[128:143]
	v_mfma_f32_32x32x16_bf16 a[64:79], v[184:187], v[196:199], a[64:79]
	v_mfma_f32_32x32x16_bf16 a[0:15], v[184:187], v[200:203], a[0:15]
	ds_read_b128 v[184:187], v48 offset:9280
	ds_read_b128 v[208:211], v49 offset:96
	ds_read_b128 v[212:215], v49 offset:4704
	v_lshl_add_u64 v[50:51], v[0:1], 0, s[2:3]
	global_load_dwordx4 v[88:91], v[50:51], off
	s_waitcnt lgkmcnt(7)
	v_mfma_f32_32x32x16_bf16 a[208:223], v[204:207], v[188:191], a[208:223]
	v_mfma_f32_32x32x16_bf16 a[144:159], v[204:207], v[192:195], a[144:159]
	v_mfma_f32_32x32x16_bf16 a[80:95], v[204:207], v[196:199], a[80:95]
	v_mfma_f32_32x32x16_bf16 a[16:31], v[204:207], v[200:203], a[16:31]
	ds_read_b128 v[204:207], v48 offset:13888
	ds_read_b128 v[216:219], v49 offset:9312
	ds_read_b128 v[220:223], v49 offset:13920
	v_lshl_add_u64 v[50:51], v[2:3], 0, s[2:3]
	s_or_b32 s2, s34, 0x50000
	global_load_dwordx4 v[92:95], v[50:51], off
	s_waitcnt lgkmcnt(5)
	v_mfma_f32_32x32x16_bf16 a[224:239], v[184:187], v[188:191], a[224:239]
	v_mfma_f32_32x32x16_bf16 a[160:175], v[184:187], v[192:195], a[160:175]
	v_mfma_f32_32x32x16_bf16 a[96:111], v[184:187], v[196:199], a[96:111]
	v_mfma_f32_32x32x16_bf16 a[32:47], v[184:187], v[200:203], a[32:47]
	ds_read_b128 v[184:187], v48 offset:96
	v_lshl_add_u64 v[50:51], v[0:1], 0, s[2:3]
	global_load_dwordx4 v[96:99], v[50:51], off
	s_waitcnt lgkmcnt(3)
	v_mfma_f32_32x32x16_bf16 a[240:255], v[204:207], v[188:191], a[240:255]
	v_mfma_f32_32x32x16_bf16 a[176:191], v[204:207], v[192:195], a[176:191]
	v_mfma_f32_32x32x16_bf16 a[112:127], v[204:207], v[196:199], a[112:127]
	v_mfma_f32_32x32x16_bf16 a[48:63], v[204:207], v[200:203], a[48:63]
	ds_read_b128 v[204:207], v48 offset:4704
	v_lshl_add_u64 v[50:51], v[2:3], 0, s[2:3]
	s_or_b32 s2, s34, 0x60000
	global_load_dwordx4 v[108:111], v[50:51], off
	s_waitcnt vmcnt(19)
	ds_write_b128 v33, v[140:143]
	s_waitcnt vmcnt(18)
	ds_write_b128 v34, v[148:151]
	s_waitcnt vmcnt(17)
	ds_write_b128 v35, v[152:155]
	s_waitcnt vmcnt(16)
	ds_write_b128 v36, v[156:159]
	s_waitcnt lgkmcnt(5)
	v_mfma_f32_32x32x16_bf16 a[192:207], v[184:187], v[208:211], a[192:207]
	v_mfma_f32_32x32x16_bf16 a[128:143], v[184:187], v[212:215], a[128:143]
	v_mfma_f32_32x32x16_bf16 a[64:79], v[184:187], v[216:219], a[64:79]
	v_mfma_f32_32x32x16_bf16 a[0:15], v[184:187], v[220:223], a[0:15]
	ds_read_b128 v[184:187], v48 offset:9312
	v_lshl_add_u64 v[50:51], v[0:1], 0, s[2:3]
	global_load_dwordx4 v[124:127], v[50:51], off
	s_waitcnt lgkmcnt(5)
	v_mfma_f32_32x32x16_bf16 a[208:223], v[204:207], v[208:211], a[208:223]
	v_mfma_f32_32x32x16_bf16 a[144:159], v[204:207], v[212:215], a[144:159]
	v_mfma_f32_32x32x16_bf16 a[80:95], v[204:207], v[216:219], a[80:95]
	v_mfma_f32_32x32x16_bf16 a[16:31], v[204:207], v[220:223], a[16:31]
	ds_read_b128 v[204:207], v48 offset:13920
	v_lshl_add_u64 v[50:51], v[2:3], 0, s[2:3]
	s_or_b32 s34, s34, 0x70000
	global_load_dwordx4 v[144:147], v[50:51], off
	s_waitcnt lgkmcnt(1)
	v_mfma_f32_32x32x16_bf16 a[224:239], v[184:187], v[208:211], a[224:239]
	v_mfma_f32_32x32x16_bf16 a[160:175], v[184:187], v[212:215], a[160:175]
	v_mfma_f32_32x32x16_bf16 a[96:111], v[184:187], v[216:219], a[96:111]
	v_mfma_f32_32x32x16_bf16 a[32:47], v[184:187], v[220:223], a[32:47]
	v_lshl_add_u64 v[50:51], v[0:1], 0, s[34:35]
	global_load_dwordx4 v[160:163], v[50:51], off
	s_waitcnt lgkmcnt(0)
	v_mfma_f32_32x32x16_bf16 a[240:255], v[204:207], v[208:211], a[240:255]
	v_mfma_f32_32x32x16_bf16 a[176:191], v[204:207], v[212:215], a[176:191]
	v_mfma_f32_32x32x16_bf16 a[112:127], v[204:207], v[216:219], a[112:127]
	v_mfma_f32_32x32x16_bf16 a[48:63], v[204:207], v[220:223], a[48:63]
	v_lshl_add_u64 v[50:51], v[2:3], 0, s[34:35]
	global_load_dwordx4 v[180:183], v[50:51], off
	s_waitcnt vmcnt(19)
	ds_write_b128 v43, v[164:167]
	s_waitcnt vmcnt(18)
	ds_write_b128 v44, v[168:171]
	s_waitcnt vmcnt(17)
	ds_write_b128 v45, v[172:175]
	s_waitcnt vmcnt(16)
	ds_write_b128 v46, v[176:179]

; #define GLOAD(RA, RB, kt) { _Pragma("unroll") for (int i = 0; i < 8; ++i) { const int ia = (tail && i >= 4) ? i - 4 : i; \
;     RA[i] = *(const u32x4*)(abase + ((size_t)(32 * ia) * lda + (kt) * 64) * 2 + aoff); RB[i] = *(const u32x4*)(bbase + ((size_t)(32 * i) * K + (kt) * 64) * 2 + boff); } }
; #define LWRITE(RA, RB, buf) { char* as_ = lds + (buf) * 2 * G_TILE; char* bs_ = as_ + G_TILE; _Pragma("unroll") for (int i = 0; i < 8; ++i) { *(u32x4*)(as_ + (lrow + 32 * i) * GS_B + lch * 16) = RA[i]; *(u32x4*)(bs_ + (lrow + 32 * i) * GS_B + lch * 16) = RB[i]; } }
; template <int EPI>
; DEV void gemm_tile(CParams& p, int layer, const bf16_t* __restrict__ A, int lda, const bf16_t* __restrict__ Bt, int K, int m0, int n0, int nt, char* lds, const int swave) {
;     ...
;   const char* asr = lds + (wm * 128 + lr) * GS_B + hh * 16;
;   const char* bsr = lds + G_TILE + (wn * 128 + lr) * GS_B + hh * 16;
;   char* wsw = lds + lrow * GS_B + lch * 16;
;     ...
;   GLOAD(ra0, rb0, 0); GLOAD(ra1, rb1, 1); LWRITE(ra0, rb0, 0); __syncthreads();
; #pragma unroll 1
;   for (int kt = 0; kt < nk; kt += 2) {
;     if (kt + 2 < nk) GLOAD(ra0, rb0, kt + 2);
;     COMPUTE(0, ra1, rb1, 1, true);
;     __syncthreads();
;     const bool more = kt + 2 < nk;
;     if (kt + 3 < nk) GLOAD(ra1, rb1, kt + 3);
;     COMPUTE(1, ra0, rb0, 0, more);
;     __syncthreads();
.LBB0_119:
	v_add_u32_e32 v224, 0x1b000, v29
	v_add_u32_e32 v225, 0x12000, v49
	s_andn2_b64 vcc, exec, s[60:61]
	s_cbranch_vccnz .Lpg_i1_nomore
	ds_read_b128 v[188:191], v225
	ds_read_b128 v[192:195], v225 offset:4608
	ds_read_b128 v[196:199], v225 offset:9216
	ds_read_b128 v[200:203], v225 offset:13824
	ds_read_b128 v[184:187], v224
	ds_read_b128 v[204:207], v224 offset:4608
	s_waitcnt lgkmcnt(1)
	v_mfma_f32_32x32x16_bf16 a[192:207], v[184:187], v[188:191], a[192:207]
	v_mfma_f32_32x32x16_bf16 a[128:143], v[184:187], v[192:195], a[128:143]
	v_mfma_f32_32x32x16_bf16 a[64:79], v[184:187], v[196:199], a[64:79]
	v_mfma_f32_32x32x16_bf16 a[0:15], v[184:187], v[200:203], a[0:15]
	ds_read_b128 v[184:187], v224 offset:9216
	ds_read_b128 v[208:211], v225 offset:32
	ds_read_b128 v[212:215], v225 offset:4640
	s_lshl_b32 s34, s36, 7
	v_lshl_add_u64 v[50:51], v[0:1], 0, s[34:35]
	v_lshl_add_u64 v[64:65], v[2:3], 0, s[34:35]
	global_load_dwordx4 v[100:103], v[50:51], off offset:384
	s_waitcnt lgkmcnt(3)
	v_mfma_f32_32x32x16_bf16 a[208:223], v[204:207], v[188:191], a[208:223]
	v_mfma_f32_32x32x16_bf16 a[144:159], v[204:207], v[192:195], a[144:159]
	v_mfma_f32_32x32x16_bf16 a[80:95], v[204:207], v[196:199], a[80:95]
	v_mfma_f32_32x32x16_bf16 a[16:31], v[204:207], v[200:203], a[16:31]
	ds_read_b128 v[204:207], v224 offset:13824
	ds_read_b128 v[216:219], v225 offset:9248
	ds_read_b128 v[220:223], v225 offset:13856
	global_load_dwordx4 v[104:107], v[64:65], off offset:384
	s_waitcnt lgkmcnt(5)
	v_mfma_f32_32x32x16_bf16 a[224:239], v[184:187], v[188:191], a[224:239]
	v_mfma_f32_32x32x16_bf16 a[160:175], v[184:187], v[192:195], a[160:175]
	v_mfma_f32_32x32x16_bf16 a[96:111], v[184:187], v[196:199], a[96:111]
	v_mfma_f32_32x32x16_bf16 a[32:47], v[184:187], v[200:203], a[32:47]
	ds_read_b128 v[184:187], v224 offset:32
	v_add_co_u32_e32 v50, vcc, 0x10000, v50
	s_nop 1
	v_addc_co_u32_e32 v51, vcc, 0, v51, vcc
	v_add_co_u32_e32 v64, vcc, 0x10000, v64
	s_nop 1
	v_addc_co_u32_e32 v65, vcc, 0, v65, vcc
	global_load_dwordx4 v[112:115], v[50:51], off offset:384
	s_waitcnt lgkmcnt(3)
	v_mfma_f32_32x32x16_bf16 a[240:255], v[204:207], v[188:191], a[240:255]
	v_mfma_f32_32x32x16_bf16 a[176:191], v[204:207], v[192:195], a[176:191]
	v_mfma_f32_32x32x16_bf16 a[112:127], v[204:207], v[196:199], a[112:127]
	v_mfma_f32_32x32x16_bf16 a[48:63], v[204:207], v[200:203], a[48:63]
	ds_read_b128 v[204:207], v224 offset:4640
	global_load_dwordx4 v[116:119], v[64:65], off offset:384
	s_waitcnt vmcnt(19)
	ds_write_b128 v30, v[52:55]
	s_waitcnt vmcnt(18)
	ds_write_b128 v30, v[56:59] offset:36864
	s_waitcnt vmcnt(17)
	ds_write_b128 v30, v[60:63] offset:4608
	s_waitcnt vmcnt(16)
	ds_write_b128 v30, v[68:71] offset:41472
	s_waitcnt lgkmcnt(5)
	v_mfma_f32_32x32x16_bf16 a[192:207], v[184:187], v[208:211], a[192:207]
	v_mfma_f32_32x32x16_bf16 a[128:143], v[184:187], v[212:215], a[128:143]
	v_mfma_f32_32x32x16_bf16 a[64:79], v[184:187], v[216:219], a[64:79]
	v_mfma_f32_32x32x16_bf16 a[0:15], v[184:187], v[220:223], a[0:15]
	ds_read_b128 v[184:187], v224 offset:9248
	ds_read_b128 v[188:191], v225 offset:64
	ds_read_b128 v[192:195], v225 offset:4672
	v_lshl_add_u64 v[50:51], v[4:5], 0, s[34:35]
	v_lshl_add_u64 v[64:65], v[6:7], 0, s[34:35]
	global_load_dwordx4 v[120:123], v[50:51], off offset:384
	s_waitcnt lgkmcnt(7)
	v_mfma_f32_32x32x16_bf16 a[208:223], v[204:207], v[208:211], a[208:223]
	v_mfma_f32_32x32x16_bf16 a[144:159], v[204:207], v[212:215], a[144:159]
	v_mfma_f32_32x32x16_bf16 a[80:95], v[204:207], v[216:219], a[80:95]
	v_mfma_f32_32x32x16_bf16 a[16:31], v[204:207], v[220:223], a[16:31]
	ds_read_b128 v[204:207], v224 offset:13856
	ds_read_b128 v[196:199], v225 offset:9280
	ds_read_b128 v[200:203], v225 offset:13888
	global_load_dwordx4 v[128:131], v[64:65], off offset:384
	s_waitcnt lgkmcnt(5)
	v_mfma_f32_32x32x16_bf16 a[224:239], v[184:187], v[208:211], a[224:239]
	v_mfma_f32_32x32x16_bf16 a[160:175], v[184:187], v[212:215], a[160:175]
	v_mfma_f32_32x32x16_bf16 a[96:111], v[184:187], v[216:219], a[96:111]
	v_mfma_f32_32x32x16_bf16 a[32:47], v[184:187], v[220:223], a[32:47]
	ds_read_b128 v[184:187], v224 offset:64
	v_lshl_add_u64 v[50:51], v[8:9], 0, s[34:35]
	v_lshl_add_u64 v[64:65], v[10:11], 0, s[34:35]
	global_load_dwordx4 v[132:135], v[50:51], off offset:384
	s_waitcnt lgkmcnt(3)
	v_mfma_f32_32x32x16_bf16 a[240:255], v[204:207], v[208:211], a[240:255]
	v_mfma_f32_32x32x16_bf16 a[176:191], v[204:207], v[212:215], a[176:191]
	v_mfma_f32_32x32x16_bf16 a[112:127], v[204:207], v[216:219], a[112:127]
	v_mfma_f32_32x32x16_bf16 a[48:63], v[204:207], v[220:223], a[48:63]
	ds_read_b128 v[204:207], v224 offset:4672
	global_load_dwordx4 v[136:139], v[64:65], off offset:384
	s_waitcnt vmcnt(19)
; #define GLOAD(RA, RB, kt) { _Pragma("unroll") for (int i = 0; i < 8; ++i) { const int ia = (tail && i >= 4) ? i - 4 : i; \
;     RA[i] = *(const u32x4*)(abase + ((size_t)(32 * ia) * lda + (kt) * 64) * 2 + aoff); RB[i] = *(const u32x4*)(bbase + ((size_t)(32 * i) * K + (kt) * 64) * 2 + boff); } }
; #define LWRITE(RA, RB, buf) { char* as_ = lds + (buf) * 2 * G_TILE; char* bs_ = as_ + G_TILE; _Pragma("unroll") for (int i = 0; i < 8; ++i) { *(u32x4*)(as_ + (lrow + 32 * i) * GS_B + lch * 16) = RA[i]; *(u32x4*)(bs_ + (lrow + 32 * i) * GS_B + lch * 16) = RB[i]; } }
; template <int EPI>
; DEV void gemm_tile(CParams& p, int layer, const bf16_t* __restrict__ A, int lda, const bf16_t* __restrict__ Bt, int K, int m0, int n0, int nt, char* lds, const int swave) {
;     ...
;   GLOAD(ra0, rb0, 0); GLOAD(ra1, rb1, 1); LWRITE(ra0, rb0, 0); __syncthreads();
; #pragma unroll 1
;   for (int kt = 0; kt < nk; kt += 2) {
;     if (kt + 2 < nk) GLOAD(ra0, rb0, kt + 2);
;     COMPUTE(0, ra1, rb1, 1, true);
;     __syncthreads();
;     const bool more = kt + 2 < nk;
;     if (kt + 3 < nk) GLOAD(ra1, rb1, kt + 3);
;     COMPUTE(1, ra0, rb0, 0, more);
;     __syncthreads();
;   }
	ds_write_b128 v30, v[72:75] offset:9216
	s_waitcnt vmcnt(18)
	ds_write_b128 v30, v[76:79] offset:46080
	s_waitcnt vmcnt(17)
	ds_write_b128 v30, v[80:83] offset:13824
	s_waitcnt vmcnt(16)
	ds_write_b128 v30, v[84:87] offset:50688
	s_waitcnt lgkmcnt(5)
	v_mfma_f32_32x32x16_bf16 a[192:207], v[184:187], v[188:191], a[192:207]
	v_mfma_f32_32x32x16_bf16 a[128:143], v[184:187], v[192:195], a[128:143]
	v_mfma_f32_32x32x16_bf16 a[64:79], v[184:187], v[196:199], a[64:79]
	v_mfma_f32_32x32x16_bf16 a[0:15], v[184:187], v[200:203], a[0:15]
	ds_read_b128 v[184:187], v224 offset:9280
	ds_read_b128 v[208:211], v225 offset:96
	ds_read_b128 v[212:215], v225 offset:4704
	v_lshl_add_u64 v[50:51], v[12:13], 0, s[34:35]
	v_lshl_add_u64 v[64:65], v[14:15], 0, s[34:35]
	global_load_dwordx4 v[140:143], v[50:51], off offset:384
	s_waitcnt lgkmcnt(7)
	v_mfma_f32_32x32x16_bf16 a[208:223], v[204:207], v[188:191], a[208:223]
	v_mfma_f32_32x32x16_bf16 a[144:159], v[204:207], v[192:195], a[144:159]
	v_mfma_f32_32x32x16_bf16 a[80:95], v[204:207], v[196:199], a[80:95]
	v_mfma_f32_32x32x16_bf16 a[16:31], v[204:207], v[200:203], a[16:31]
	ds_read_b128 v[204:207], v224 offset:13888
	ds_read_b128 v[216:219], v225 offset:9312
	ds_read_b128 v[220:223], v225 offset:13920
	global_load_dwordx4 v[148:151], v[64:65], off offset:384
	s_waitcnt lgkmcnt(5)
	v_mfma_f32_32x32x16_bf16 a[224:239], v[184:187], v[188:191], a[224:239]
	v_mfma_f32_32x32x16_bf16 a[160:175], v[184:187], v[192:195], a[160:175]
	v_mfma_f32_32x32x16_bf16 a[96:111], v[184:187], v[196:199], a[96:111]
	v_mfma_f32_32x32x16_bf16 a[32:47], v[184:187], v[200:203], a[32:47]
	ds_read_b128 v[184:187], v224 offset:96
	v_lshl_add_u64 v[50:51], v[16:17], 0, s[34:35]
	v_lshl_add_u64 v[64:65], v[18:19], 0, s[34:35]
	global_load_dwordx4 v[152:155], v[50:51], off offset:384
	s_waitcnt lgkmcnt(3)
	v_mfma_f32_32x32x16_bf16 a[240:255], v[204:207], v[188:191], a[240:255]
	v_mfma_f32_32x32x16_bf16 a[176:191], v[204:207], v[192:195], a[176:191]
	v_mfma_f32_32x32x16_bf16 a[112:127], v[204:207], v[196:199], a[112:127]
	v_mfma_f32_32x32x16_bf16 a[48:63], v[204:207], v[200:203], a[48:63]
	ds_read_b128 v[204:207], v224 offset:4704
	global_load_dwordx4 v[156:159], v[64:65], off offset:384
	s_waitcnt vmcnt(19)
	ds_write_b128 v30, v[88:91] offset:18432
	s_waitcnt vmcnt(18)
	ds_write_b128 v30, v[92:95] offset:55296
	s_waitcnt vmcnt(17)
	ds_write_b128 v30, v[96:99] offset:23040
	s_waitcnt vmcnt(16)
	ds_write_b128 v30, v[108:111] offset:59904
	s_waitcnt lgkmcnt(5)
	v_mfma_f32_32x32x16_bf16 a[192:207], v[184:187], v[208:211], a[192:207]
	v_mfma_f32_32x32x16_bf16 a[128:143], v[184:187], v[212:215], a[128:143]
	v_mfma_f32_32x32x16_bf16 a[64:79], v[184:187], v[216:219], a[64:79]
	v_mfma_f32_32x32x16_bf16 a[0:15], v[184:187], v[220:223], a[0:15]
	ds_read_b128 v[184:187], v224 offset:9312
	v_lshl_add_u64 v[50:51], v[20:21], 0, s[34:35]
	v_lshl_add_u64 v[64:65], v[22:23], 0, s[34:35]
	global_load_dwordx4 v[164:167], v[50:51], off offset:384
	s_waitcnt lgkmcnt(5)
	v_mfma_f32_32x32x16_bf16 a[208:223], v[204:207], v[208:211], a[208:223]
	v_mfma_f32_32x32x16_bf16 a[144:159], v[204:207], v[212:215], a[144:159]
	v_mfma_f32_32x32x16_bf16 a[80:95], v[204:207], v[216:219], a[80:95]
	v_mfma_f32_32x32x16_bf16 a[16:31], v[204:207], v[220:223], a[16:31]
	ds_read_b128 v[204:207], v224 offset:13920
	global_load_dwordx4 v[168:171], v[64:65], off offset:384
	s_waitcnt lgkmcnt(1)
	v_mfma_f32_32x32x16_bf16 a[224:239], v[184:187], v[208:211], a[224:239]
	v_mfma_f32_32x32x16_bf16 a[160:175], v[184:187], v[212:215], a[160:175]
	v_mfma_f32_32x32x16_bf16 a[96:111], v[184:187], v[216:219], a[96:111]
	v_mfma_f32_32x32x16_bf16 a[32:47], v[184:187], v[220:223], a[32:47]
	v_lshl_add_u64 v[50:51], v[24:25], 0, s[34:35]
	v_lshl_add_u64 v[64:65], v[26:27], 0, s[34:35]
	global_load_dwordx4 v[172:175], v[50:51], off offset:384
	s_waitcnt lgkmcnt(0)
	v_mfma_f32_32x32x16_bf16 a[240:255], v[204:207], v[208:211], a[240:255]
	v_mfma_f32_32x32x16_bf16 a[176:191], v[204:207], v[212:215], a[176:191]
	v_mfma_f32_32x32x16_bf16 a[112:127], v[204:207], v[216:219], a[112:127]
	v_mfma_f32_32x32x16_bf16 a[48:63], v[204:207], v[220:223], a[48:63]
	global_load_dwordx4 v[176:179], v[64:65], off offset:384
	s_waitcnt vmcnt(19)
	ds_write_b128 v30, v[124:127] offset:27648
	s_waitcnt vmcnt(18)
	ds_write_b128 v30, v[144:147] offset:64512
	s_waitcnt vmcnt(17)
	ds_write_b128 v30, v[160:163] offset:32256
	s_waitcnt vmcnt(16)
	ds_write_b128 v47, v[180:183]
	s_branch .LBB0_98

; #define GLOAD(RA, RB, kt) { _Pragma("unroll") for (int i = 0; i < 8; ++i) { const int ia = (tail && i >= 4) ? i - 4 : i; \
;     RA[i] = *(const u32x4*)(abase + ((size_t)(32 * ia) * lda + (kt) * 64) * 2 + aoff); RB[i] = *(const u32x4*)(bbase + ((size_t)(32 * i) * K + (kt) * 64) * 2 + boff); } }
; #define LWRITE(RA, RB, buf) { char* as_ = lds + (buf) * 2 * G_TILE; char* bs_ = as_ + G_TILE; _Pragma("unroll") for (int i = 0; i < 8; ++i) { *(u32x4*)(as_ + (lrow + 32 * i) * GS_B + lch * 16) = RA[i]; *(u32x4*)(bs_ + (lrow + 32 * i) * GS_B + lch * 16) = RB[i]; } }
; template <int EPI>
; DEV void gemm_tile(CParams& p, int layer, const bf16_t* __restrict__ A, int lda, const bf16_t* __restrict__ Bt, int K, int m0, int n0, int nt, char* lds, const int swave) {
;     ...
;   const char* asr = lds + (wm * 128 + lr) * GS_B + hh * 16;
;   const char* bsr = lds + G_TILE + (wn * 128 + lr) * GS_B + hh * 16;
;   char* wsw = lds + lrow * GS_B + lch * 16;
;     ...
;   GLOAD(ra0, rb0, 0); GLOAD(ra1, rb1, 1); LWRITE(ra0, rb0, 0); __syncthreads();
; #pragma unroll 1
;   for (int kt = 0; kt < nk; kt += 2) {
;     if (kt + 2 < nk) GLOAD(ra0, rb0, kt + 2);
;     COMPUTE(0, ra1, rb1, 1, true);
;     __syncthreads();
.LBB0_161:
	s_cmp_eq_u32 s86, 0
	s_cbranch_scc0 .Lzi_i2
	ds_read_b128 v[164:167], v26
	ds_read_b128 v[168:171], v26 offset:4608
	ds_read_b128 v[172:175], v26 offset:9216
	ds_read_b128 v[176:179], v26 offset:13824
	ds_read_b128 v[160:163], v25
	ds_read_b128 v[180:183], v25 offset:4608
	s_waitcnt lgkmcnt(1)
	v_mfma_f32_32x32x16_bf16 a[96:111], v[160:163], v[164:167], 0
	v_mfma_f32_32x32x16_bf16 a[0:15], v[160:163], v[168:171], 0
	v_mfma_f32_32x32x16_bf16 a[16:31], v[160:163], v[172:175], 0
	v_mfma_f32_32x32x16_bf16 a[32:47], v[160:163], v[176:179], 0
	ds_read_b128 v[160:163], v25 offset:9216
	ds_read_b128 v[184:187], v26 offset:32
	ds_read_b128 v[188:191], v26 offset:4640
	v_lshl_add_u64 v[28:29], v[2:3], 0, s[34:35]
	v_lshl_add_u64 v[30:31], v[4:5], 0, s[34:35]
	s_add_i32 s2, s100, s28
	s_lshl_b32 s44, s100, 6
	global_load_dwordx4 v[32:35], v[28:29], off
	s_waitcnt lgkmcnt(3)
	v_mfma_f32_32x32x16_bf16 a[80:95], v[180:183], v[164:167], 0
	v_mfma_f32_32x32x16_bf16 a[48:63], v[180:183], v[168:171], 0
	v_mfma_f32_32x32x16_bf16 a[64:79], v[180:183], v[172:175], 0
	v_mfma_f32_32x32x16_bf16 a[112:127], v[180:183], v[176:179], 0
	ds_read_b128 v[180:183], v25 offset:13824
	ds_read_b128 v[192:195], v26 offset:9248
	ds_read_b128 v[196:199], v26 offset:13856
	global_load_dwordx4 v[36:39], v[30:31], off
	s_waitcnt lgkmcnt(5)
	v_mfma_f32_32x32x16_bf16 a[128:143], v[160:163], v[164:167], 0
	v_mfma_f32_32x32x16_bf16 a[144:159], v[160:163], v[168:171], 0
	v_mfma_f32_32x32x16_bf16 a[160:175], v[160:163], v[172:175], 0
	v_mfma_f32_32x32x16_bf16 a[176:191], v[160:163], v[176:179], 0
	ds_read_b128 v[160:163], v25 offset:32
	v_lshl_add_u64 v[28:29], v[28:29], 0, s[8:9]
	v_lshl_add_u64 v[30:31], v[30:31], 0, s[8:9]
	s_lshl_b32 s2, s2, 7
	s_mov_b32 s3, s35
	global_load_dwordx4 v[40:43], v[28:29], off
	s_waitcnt lgkmcnt(3)
	v_mfma_f32_32x32x16_bf16 a[192:207], v[180:183], v[164:167], 0
	v_mfma_f32_32x32x16_bf16 a[208:223], v[180:183], v[168:171], 0
	v_mfma_f32_32x32x16_bf16 a[224:239], v[180:183], v[172:175], 0
	v_mfma_f32_32x32x16_bf16 a[240:255], v[180:183], v[176:179], 0
	ds_read_b128 v[180:183], v25 offset:4640
	global_load_dwordx4 v[44:47], v[30:31], off
	s_waitcnt vmcnt(19)
	ds_write_b128 v8, v[84:87]
	s_waitcnt vmcnt(18)
	ds_write_b128 v9, v[88:91]
	s_waitcnt vmcnt(17)
	ds_write_b128 v18, v[96:99]
	s_waitcnt vmcnt(16)
	ds_write_b128 v19, v[104:107]
	s_waitcnt lgkmcnt(5)
	v_mfma_f32_32x32x16_bf16 a[96:111], v[160:163], v[184:187], a[96:111]
	v_mfma_f32_32x32x16_bf16 a[0:15], v[160:163], v[188:191], a[0:15]
	v_mfma_f32_32x32x16_bf16 a[16:31], v[160:163], v[192:195], a[16:31]
	v_mfma_f32_32x32x16_bf16 a[32:47], v[160:163], v[196:199], a[32:47]
	ds_read_b128 v[160:163], v25 offset:9248
	ds_read_b128 v[164:167], v26 offset:64
	ds_read_b128 v[168:171], v26 offset:4672
	v_lshl_add_u64 v[28:29], v[2:3], 0, s[2:3]
	v_lshl_add_u64 v[30:31], v[4:5], 0, s[2:3]
	s_add_i32 s2, s44, s38
	s_lshl_b32 s2, s2, 1
	global_load_dwordx4 v[48:51], v[28:29], off
	s_waitcnt lgkmcnt(7)
	v_mfma_f32_32x32x16_bf16 a[80:95], v[180:183], v[184:187], a[80:95]
	v_mfma_f32_32x32x16_bf16 a[48:63], v[180:183], v[188:191], a[48:63]
	v_mfma_f32_32x32x16_bf16 a[64:79], v[180:183], v[192:195], a[64:79]
	v_mfma_f32_32x32x16_bf16 a[112:127], v[180:183], v[196:199], a[112:127]
	ds_read_b128 v[180:183], v25 offset:13856
	ds_read_b128 v[172:175], v26 offset:9280
	ds_read_b128 v[176:179], v26 offset:13888
	global_load_dwordx4 v[52:55], v[30:31], off
	s_waitcnt lgkmcnt(5)
	v_mfma_f32_32x32x16_bf16 a[128:143], v[160:163], v[184:187], a[128:143]
	v_mfma_f32_32x32x16_bf16 a[144:159], v[160:163], v[188:191], a[144:159]
	v_mfma_f32_32x32x16_bf16 a[160:175], v[160:163], v[192:195], a[160:175]
	v_mfma_f32_32x32x16_bf16 a[176:191], v[160:163], v[196:199], a[176:191]
	ds_read_b128 v[160:163], v25 offset:64
	v_lshl_add_u64 v[28:29], v[2:3], 0, s[2:3]
	v_lshl_add_u64 v[30:31], v[4:5], 0, s[2:3]
	s_add_i32 s34, s34, s91
	s_add_i32 s2, s44, s39
	global_load_dwordx4 v[56:59], v[28:29], off
	s_waitcnt lgkmcnt(3)
	v_mfma_f32_32x32x16_bf16 a[192:207], v[180:183], v[184:187], a[192:207]
	v_mfma_f32_32x32x16_bf16 a[208:223], v[180:183], v[188:191], a[208:223]
	v_mfma_f32_32x32x16_bf16 a[224:239], v[180:183], v[192:195], a[224:239]
	v_mfma_f32_32x32x16_bf16 a[240:255], v[180:183], v[196:199], a[240:255]
	ds_read_b128 v[180:183], v25 offset:4672
	global_load_dwordx4 v[60:63], v[30:31], off
	s_waitcnt vmcnt(19)
	ds_write_b128 v14, v[112:115]
	s_waitcnt vmcnt(18)
	ds_write_b128 v15, v[116:119]
	s_waitcnt vmcnt(17)
	ds_write_b128 v16, v[120:123]
	s_waitcnt vmcnt(16)
	ds_write_b128 v17, v[124:127]
	s_waitcnt lgkmcnt(5)
	v_mfma_f32_32x32x16_bf16 a[96:111], v[160:163], v[164:167], a[96:111]
	v_mfma_f32_32x32x16_bf16 a[0:15], v[160:163], v[168:171], a[0:15]
	v_mfma_f32_32x32x16_bf16 a[16:31], v[160:163], v[172:175], a[16:31]
	v_mfma_f32_32x32x16_bf16 a[32:47], v[160:163], v[176:179], a[32:47]
	ds_read_b128 v[160:163], v25 offset:9280
	ds_read_b128 v[184:187], v26 offset:96
	ds_read_b128 v[188:191], v26 offset:4704
	v_lshl_add_u64 v[28:29], v[2:3], 0, s[34:35]
	v_lshl_add_u64 v[30:31], v[4:5], 0, s[34:35]
	s_lshl_b32 s34, s2, 1
	s_add_i32 s2, s44, s68
	global_load_dwordx4 v[64:67], v[28:29], off
	s_waitcnt lgkmcnt(7)
	v_mfma_f32_32x32x16_bf16 a[80:95], v[180:183], v[164:167], a[80:95]
	v_mfma_f32_32x32x16_bf16 a[48:63], v[180:183], v[168:171], a[48:63]
	v_mfma_f32_32x32x16_bf16 a[64:79], v[180:183], v[172:175], a[64:79]
	v_mfma_f32_32x32x16_bf16 a[112:127], v[180:183], v[176:179], a[112:127]
	ds_read_b128 v[180:183], v25 offset:13888
	ds_read_b128 v[192:195], v26 offset:9312
	ds_read_b128 v[196:199], v26 offset:13920
	global_load_dwordx4 v[68:71], v[30:31], off
	s_waitcnt lgkmcnt(5)
; #define GLOAD(RA, RB, kt) { _Pragma("unroll") for (int i = 0; i < 8; ++i) { const int ia = (tail && i >= 4) ? i - 4 : i; \
;     RA[i] = *(const u32x4*)(abase + ((size_t)(32 * ia) * lda + (kt) * 64) * 2 + aoff); RB[i] = *(const u32x4*)(bbase + ((size_t)(32 * i) * K + (kt) * 64) * 2 + boff); } }
; #define LWRITE(RA, RB, buf) { char* as_ = lds + (buf) * 2 * G_TILE; char* bs_ = as_ + G_TILE; _Pragma("unroll") for (int i = 0; i < 8; ++i) { *(u32x4*)(as_ + (lrow + 32 * i) * GS_B + lch * 16) = RA[i]; *(u32x4*)(bs_ + (lrow + 32 * i) * GS_B + lch * 16) = RB[i]; } }
; template <int EPI>
; DEV void gemm_tile(CParams& p, int layer, const bf16_t* __restrict__ A, int lda, const bf16_t* __restrict__ Bt, int K, int m0, int n0, int nt, char* lds, const int swave) {
;     ...
;   const char* asr = lds + (wm * 128 + lr) * GS_B + hh * 16;
;   const char* bsr = lds + G_TILE + (wn * 128 + lr) * GS_B + hh * 16;
;   char* wsw = lds + lrow * GS_B + lch * 16;
;     ...
;   GLOAD(ra0, rb0, 0); GLOAD(ra1, rb1, 1); LWRITE(ra0, rb0, 0); __syncthreads();
; #pragma unroll 1
;   for (int kt = 0; kt < nk; kt += 2) {
;     if (kt + 2 < nk) GLOAD(ra0, rb0, kt + 2);
;     COMPUTE(0, ra1, rb1, 1, true);
;     __syncthreads();
	v_mfma_f32_32x32x16_bf16 a[128:143], v[160:163], v[164:167], a[128:143]
	v_mfma_f32_32x32x16_bf16 a[144:159], v[160:163], v[168:171], a[144:159]
	v_mfma_f32_32x32x16_bf16 a[160:175], v[160:163], v[172:175], a[160:175]
	v_mfma_f32_32x32x16_bf16 a[176:191], v[160:163], v[176:179], a[176:191]
	ds_read_b128 v[160:163], v25 offset:96
	v_lshl_add_u64 v[28:29], v[2:3], 0, s[34:35]
	v_lshl_add_u64 v[30:31], v[4:5], 0, s[34:35]
	s_lshl_b32 s34, s2, 1
	s_add_i32 s44, s44, s40
	global_load_dwordx4 v[72:75], v[28:29], off
	s_waitcnt lgkmcnt(3)
	v_mfma_f32_32x32x16_bf16 a[192:207], v[180:183], v[164:167], a[192:207]
	v_mfma_f32_32x32x16_bf16 a[208:223], v[180:183], v[168:171], a[208:223]
	v_mfma_f32_32x32x16_bf16 a[224:239], v[180:183], v[172:175], a[224:239]
	v_mfma_f32_32x32x16_bf16 a[240:255], v[180:183], v[176:179], a[240:255]
	ds_read_b128 v[180:183], v25 offset:4704
	global_load_dwordx4 v[76:79], v[30:31], off
	s_waitcnt vmcnt(19)
	ds_write_b128 v10, v[128:131]
	s_waitcnt vmcnt(18)
	ds_write_b128 v11, v[132:135]
	s_waitcnt vmcnt(17)
	ds_write_b128 v12, v[136:139]
	s_waitcnt vmcnt(16)
	ds_write_b128 v13, v[140:143]
	s_waitcnt lgkmcnt(5)
	v_mfma_f32_32x32x16_bf16 a[96:111], v[160:163], v[184:187], a[96:111]
	v_mfma_f32_32x32x16_bf16 a[0:15], v[160:163], v[188:191], a[0:15]
	v_mfma_f32_32x32x16_bf16 a[16:31], v[160:163], v[192:195], a[16:31]
	v_mfma_f32_32x32x16_bf16 a[32:47], v[160:163], v[196:199], a[32:47]
	ds_read_b128 v[160:163], v25 offset:9312
	v_lshl_add_u64 v[28:29], v[2:3], 0, s[34:35]
	v_lshl_add_u64 v[30:31], v[4:5], 0, s[34:35]
	s_lshl_b32 s34, s44, 1
	global_load_dwordx4 v[80:83], v[28:29], off
	s_waitcnt lgkmcnt(5)
	v_mfma_f32_32x32x16_bf16 a[80:95], v[180:183], v[184:187], a[80:95]
	v_mfma_f32_32x32x16_bf16 a[48:63], v[180:183], v[188:191], a[48:63]
	v_mfma_f32_32x32x16_bf16 a[64:79], v[180:183], v[192:195], a[64:79]
	v_mfma_f32_32x32x16_bf16 a[112:127], v[180:183], v[196:199], a[112:127]
	ds_read_b128 v[180:183], v25 offset:13920
	global_load_dwordx4 v[92:95], v[30:31], off
	s_waitcnt lgkmcnt(1)
	v_mfma_f32_32x32x16_bf16 a[128:143], v[160:163], v[184:187], a[128:143]
	v_mfma_f32_32x32x16_bf16 a[144:159], v[160:163], v[188:191], a[144:159]
	v_mfma_f32_32x32x16_bf16 a[160:175], v[160:163], v[192:195], a[160:175]
	v_mfma_f32_32x32x16_bf16 a[176:191], v[160:163], v[196:199], a[176:191]
	v_lshl_add_u64 v[28:29], v[2:3], 0, s[34:35]
	v_lshl_add_u64 v[30:31], v[4:5], 0, s[34:35]
	global_load_dwordx4 v[100:103], v[28:29], off
	s_waitcnt lgkmcnt(0)
	v_mfma_f32_32x32x16_bf16 a[192:207], v[180:183], v[184:187], a[192:207]
	v_mfma_f32_32x32x16_bf16 a[208:223], v[180:183], v[188:191], a[208:223]
	v_mfma_f32_32x32x16_bf16 a[224:239], v[180:183], v[192:195], a[224:239]
	v_mfma_f32_32x32x16_bf16 a[240:255], v[180:183], v[196:199], a[240:255]
	global_load_dwordx4 v[108:111], v[30:31], off
	s_waitcnt vmcnt(19)
	ds_write_b128 v20, v[144:147]
	s_waitcnt vmcnt(18)
	ds_write_b128 v21, v[148:151]
	s_waitcnt vmcnt(17)
	ds_write_b128 v22, v[152:155]
	s_waitcnt vmcnt(16)
	ds_write_b128 v23, v[156:159]
	s_branch .LBB0_177
.Lzi_i2:
	ds_read_b128 v[164:167], v26
	ds_read_b128 v[168:171], v26 offset:4608
	ds_read_b128 v[172:175], v26 offset:9216
	ds_read_b128 v[176:179], v26 offset:13824
	ds_read_b128 v[160:163], v25
	ds_read_b128 v[180:183], v25 offset:4608
	s_waitcnt lgkmcnt(1)
	v_mfma_f32_32x32x16_bf16 a[96:111], v[160:163], v[164:167], a[96:111]
	v_mfma_f32_32x32x16_bf16 a[0:15], v[160:163], v[168:171], a[0:15]
	v_mfma_f32_32x32x16_bf16 a[16:31], v[160:163], v[172:175], a[16:31]
	v_mfma_f32_32x32x16_bf16 a[32:47], v[160:163], v[176:179], a[32:47]
	ds_read_b128 v[160:163], v25 offset:9216
	ds_read_b128 v[184:187], v26 offset:32
	ds_read_b128 v[188:191], v26 offset:4640
	v_lshl_add_u64 v[28:29], v[2:3], 0, s[34:35]
	v_lshl_add_u64 v[30:31], v[4:5], 0, s[34:35]
	s_add_i32 s2, s100, s28
	s_lshl_b32 s44, s100, 6
	global_load_dwordx4 v[32:35], v[28:29], off
	s_waitcnt lgkmcnt(3)
	v_mfma_f32_32x32x16_bf16 a[80:95], v[180:183], v[164:167], a[80:95]
	v_mfma_f32_32x32x16_bf16 a[48:63], v[180:183], v[168:171], a[48:63]
	v_mfma_f32_32x32x16_bf16 a[64:79], v[180:183], v[172:175], a[64:79]
	v_mfma_f32_32x32x16_bf16 a[112:127], v[180:183], v[176:179], a[112:127]
	ds_read_b128 v[180:183], v25 offset:13824
	ds_read_b128 v[192:195], v26 offset:9248
	ds_read_b128 v[196:199], v26 offset:13856
	global_load_dwordx4 v[36:39], v[30:31], off
	s_waitcnt lgkmcnt(5)
	v_mfma_f32_32x32x16_bf16 a[128:143], v[160:163], v[164:167], a[128:143]
	v_mfma_f32_32x32x16_bf16 a[144:159], v[160:163], v[168:171], a[144:159]
	v_mfma_f32_32x32x16_bf16 a[160:175], v[160:163], v[172:175], a[160:175]
	v_mfma_f32_32x32x16_bf16 a[176:191], v[160:163], v[176:179], a[176:191]
	ds_read_b128 v[160:163], v25 offset:32
	v_lshl_add_u64 v[28:29], v[28:29], 0, s[8:9]
	v_lshl_add_u64 v[30:31], v[30:31], 0, s[8:9]
	s_lshl_b32 s2, s2, 7
	s_mov_b32 s3, s35
	global_load_dwordx4 v[40:43], v[28:29], off
	s_waitcnt lgkmcnt(3)
	v_mfma_f32_32x32x16_bf16 a[192:207], v[180:183], v[164:167], a[192:207]
	v_mfma_f32_32x32x16_bf16 a[208:223], v[180:183], v[168:171], a[208:223]
	v_mfma_f32_32x32x16_bf16 a[224:239], v[180:183], v[172:175], a[224:239]
	v_mfma_f32_32x32x16_bf16 a[240:255], v[180:183], v[176:179], a[240:255]
	ds_read_b128 v[180:183], v25 offset:4640
	global_load_dwordx4 v[44:47], v[30:31], off
	s_waitcnt vmcnt(19)
	ds_write_b128 v8, v[84:87]
	s_waitcnt vmcnt(18)
	ds_write_b128 v9, v[88:91]
	s_waitcnt vmcnt(17)
	ds_write_b128 v18, v[96:99]
	s_waitcnt vmcnt(16)
	ds_write_b128 v19, v[104:107]
	s_waitcnt lgkmcnt(5)
; #define GLOAD(RA, RB, kt) { _Pragma("unroll") for (int i = 0; i < 8; ++i) { const int ia = (tail && i >= 4) ? i - 4 : i; \
;     RA[i] = *(const u32x4*)(abase + ((size_t)(32 * ia) * lda + (kt) * 64) * 2 + aoff); RB[i] = *(const u32x4*)(bbase + ((size_t)(32 * i) * K + (kt) * 64) * 2 + boff); } }
; #define LWRITE(RA, RB, buf) { char* as_ = lds + (buf) * 2 * G_TILE; char* bs_ = as_ + G_TILE; _Pragma("unroll") for (int i = 0; i < 8; ++i) { *(u32x4*)(as_ + (lrow + 32 * i) * GS_B + lch * 16) = RA[i]; *(u32x4*)(bs_ + (lrow + 32 * i) * GS_B + lch * 16) = RB[i]; } }
; template <int EPI>
; DEV void gemm_tile(CParams& p, int layer, const bf16_t* __restrict__ A, int lda, const bf16_t* __restrict__ Bt, int K, int m0, int n0, int nt, char* lds, const int swave) {
;     ...
;   GLOAD(ra0, rb0, 0); GLOAD(ra1, rb1, 1); LWRITE(ra0, rb0, 0); __syncthreads();
; #pragma unroll 1
;   for (int kt = 0; kt < nk; kt += 2) {
;     if (kt + 2 < nk) GLOAD(ra0, rb0, kt + 2);
;     COMPUTE(0, ra1, rb1, 1, true);
;     __syncthreads();
	v_mfma_f32_32x32x16_bf16 a[96:111], v[160:163], v[184:187], a[96:111]
	v_mfma_f32_32x32x16_bf16 a[0:15], v[160:163], v[188:191], a[0:15]
	v_mfma_f32_32x32x16_bf16 a[16:31], v[160:163], v[192:195], a[16:31]
	v_mfma_f32_32x32x16_bf16 a[32:47], v[160:163], v[196:199], a[32:47]
	ds_read_b128 v[160:163], v25 offset:9248
	ds_read_b128 v[164:167], v26 offset:64
	ds_read_b128 v[168:171], v26 offset:4672
	v_lshl_add_u64 v[28:29], v[2:3], 0, s[2:3]
	v_lshl_add_u64 v[30:31], v[4:5], 0, s[2:3]
	s_add_i32 s2, s44, s38
	s_lshl_b32 s2, s2, 1
	global_load_dwordx4 v[48:51], v[28:29], off
	s_waitcnt lgkmcnt(7)
	v_mfma_f32_32x32x16_bf16 a[80:95], v[180:183], v[184:187], a[80:95]
	v_mfma_f32_32x32x16_bf16 a[48:63], v[180:183], v[188:191], a[48:63]
	v_mfma_f32_32x32x16_bf16 a[64:79], v[180:183], v[192:195], a[64:79]
	v_mfma_f32_32x32x16_bf16 a[112:127], v[180:183], v[196:199], a[112:127]
	ds_read_b128 v[180:183], v25 offset:13856
	ds_read_b128 v[172:175], v26 offset:9280
	ds_read_b128 v[176:179], v26 offset:13888
	global_load_dwordx4 v[52:55], v[30:31], off
	s_waitcnt lgkmcnt(5)
	v_mfma_f32_32x32x16_bf16 a[128:143], v[160:163], v[184:187], a[128:143]
	v_mfma_f32_32x32x16_bf16 a[144:159], v[160:163], v[188:191], a[144:159]
	v_mfma_f32_32x32x16_bf16 a[160:175], v[160:163], v[192:195], a[160:175]
	v_mfma_f32_32x32x16_bf16 a[176:191], v[160:163], v[196:199], a[176:191]
	ds_read_b128 v[160:163], v25 offset:64
	v_lshl_add_u64 v[28:29], v[2:3], 0, s[2:3]
	v_lshl_add_u64 v[30:31], v[4:5], 0, s[2:3]
	s_add_i32 s34, s34, s91
	s_add_i32 s2, s44, s39
	global_load_dwordx4 v[56:59], v[28:29], off
	s_waitcnt lgkmcnt(3)
	v_mfma_f32_32x32x16_bf16 a[192:207], v[180:183], v[184:187], a[192:207]
	v_mfma_f32_32x32x16_bf16 a[208:223], v[180:183], v[188:191], a[208:223]
	v_mfma_f32_32x32x16_bf16 a[224:239], v[180:183], v[192:195], a[224:239]
	v_mfma_f32_32x32x16_bf16 a[240:255], v[180:183], v[196:199], a[240:255]
	ds_read_b128 v[180:183], v25 offset:4672
	global_load_dwordx4 v[60:63], v[30:31], off
	s_waitcnt vmcnt(19)
	ds_write_b128 v14, v[112:115]
	s_waitcnt vmcnt(18)
	ds_write_b128 v15, v[116:119]
	s_waitcnt vmcnt(17)
	ds_write_b128 v16, v[120:123]
	s_waitcnt vmcnt(16)
	ds_write_b128 v17, v[124:127]
	s_waitcnt lgkmcnt(5)
	v_mfma_f32_32x32x16_bf16 a[96:111], v[160:163], v[164:167], a[96:111]
	v_mfma_f32_32x32x16_bf16 a[0:15], v[160:163], v[168:171], a[0:15]
	v_mfma_f32_32x32x16_bf16 a[16:31], v[160:163], v[172:175], a[16:31]
	v_mfma_f32_32x32x16_bf16 a[32:47], v[160:163], v[176:179], a[32:47]
	ds_read_b128 v[160:163], v25 offset:9280
	ds_read_b128 v[184:187], v26 offset:96
	ds_read_b128 v[188:191], v26 offset:4704
	v_lshl_add_u64 v[28:29], v[2:3], 0, s[34:35]
	v_lshl_add_u64 v[30:31], v[4:5], 0, s[34:35]
	s_lshl_b32 s34, s2, 1
	s_add_i32 s2, s44, s68
	global_load_dwordx4 v[64:67], v[28:29], off
	s_waitcnt lgkmcnt(7)
	v_mfma_f32_32x32x16_bf16 a[80:95], v[180:183], v[164:167], a[80:95]
	v_mfma_f32_32x32x16_bf16 a[48:63], v[180:183], v[168:171], a[48:63]
	v_mfma_f32_32x32x16_bf16 a[64:79], v[180:183], v[172:175], a[64:79]
	v_mfma_f32_32x32x16_bf16 a[112:127], v[180:183], v[176:179], a[112:127]
	ds_read_b128 v[180:183], v25 offset:13888
	ds_read_b128 v[192:195], v26 offset:9312
	ds_read_b128 v[196:199], v26 offset:13920
	global_load_dwordx4 v[68:71], v[30:31], off
	s_waitcnt lgkmcnt(5)
	v_mfma_f32_32x32x16_bf16 a[128:143], v[160:163], v[164:167], a[128:143]
	v_mfma_f32_32x32x16_bf16 a[144:159], v[160:163], v[168:171], a[144:159]
	v_mfma_f32_32x32x16_bf16 a[160:175], v[160:163], v[172:175], a[160:175]
	v_mfma_f32_32x32x16_bf16 a[176:191], v[160:163], v[176:179], a[176:191]
	ds_read_b128 v[160:163], v25 offset:96
	v_lshl_add_u64 v[28:29], v[2:3], 0, s[34:35]
	v_lshl_add_u64 v[30:31], v[4:5], 0, s[34:35]
	s_lshl_b32 s34, s2, 1
	s_add_i32 s44, s44, s40
	global_load_dwordx4 v[72:75], v[28:29], off
	s_waitcnt lgkmcnt(3)
	v_mfma_f32_32x32x16_bf16 a[192:207], v[180:183], v[164:167], a[192:207]
	v_mfma_f32_32x32x16_bf16 a[208:223], v[180:183], v[168:171], a[208:223]
	v_mfma_f32_32x32x16_bf16 a[224:239], v[180:183], v[172:175], a[224:239]
	v_mfma_f32_32x32x16_bf16 a[240:255], v[180:183], v[176:179], a[240:255]
	ds_read_b128 v[180:183], v25 offset:4704
	global_load_dwordx4 v[76:79], v[30:31], off
	s_waitcnt vmcnt(19)
	ds_write_b128 v10, v[128:131]
	s_waitcnt vmcnt(18)
	ds_write_b128 v11, v[132:135]
	s_waitcnt vmcnt(17)
	ds_write_b128 v12, v[136:139]
	s_waitcnt vmcnt(16)
	ds_write_b128 v13, v[140:143]
	s_waitcnt lgkmcnt(5)
	v_mfma_f32_32x32x16_bf16 a[96:111], v[160:163], v[184:187], a[96:111]
	v_mfma_f32_32x32x16_bf16 a[0:15], v[160:163], v[188:191], a[0:15]
	v_mfma_f32_32x32x16_bf16 a[16:31], v[160:163], v[192:195], a[16:31]
	v_mfma_f32_32x32x16_bf16 a[32:47], v[160:163], v[196:199], a[32:47]
	ds_read_b128 v[160:163], v25 offset:9312
	v_lshl_add_u64 v[28:29], v[2:3], 0, s[34:35]
	v_lshl_add_u64 v[30:31], v[4:5], 0, s[34:35]
	s_lshl_b32 s34, s44, 1
	global_load_dwordx4 v[80:83], v[28:29], off
	s_waitcnt lgkmcnt(5)
	v_mfma_f32_32x32x16_bf16 a[80:95], v[180:183], v[184:187], a[80:95]
	v_mfma_f32_32x32x16_bf16 a[48:63], v[180:183], v[188:191], a[48:63]
	v_mfma_f32_32x32x16_bf16 a[64:79], v[180:183], v[192:195], a[64:79]
	v_mfma_f32_32x32x16_bf16 a[112:127], v[180:183], v[196:199], a[112:127]
	ds_read_b128 v[180:183], v25 offset:13920
	global_load_dwordx4 v[92:95], v[30:31], off
	s_waitcnt lgkmcnt(1)
	v_mfma_f32_32x32x16_bf16 a[128:143], v[160:163], v[184:187], a[128:143]
	v_mfma_f32_32x32x16_bf16 a[144:159], v[160:163], v[188:191], a[144:159]
	v_mfma_f32_32x32x16_bf16 a[160:175], v[160:163], v[192:195], a[160:175]
	v_mfma_f32_32x32x16_bf16 a[176:191], v[160:163], v[196:199], a[176:191]
	v_lshl_add_u64 v[28:29], v[2:3], 0, s[34:35]
	v_lshl_add_u64 v[30:31], v[4:5], 0, s[34:35]
	global_load_dwordx4 v[100:103], v[28:29], off
	s_waitcnt lgkmcnt(0)
	v_mfma_f32_32x32x16_bf16 a[192:207], v[180:183], v[184:187], a[192:207]
	v_mfma_f32_32x32x16_bf16 a[208:223], v[180:183], v[188:191], a[208:223]
	v_mfma_f32_32x32x16_bf16 a[224:239], v[180:183], v[192:195], a[224:239]
	v_mfma_f32_32x32x16_bf16 a[240:255], v[180:183], v[196:199], a[240:255]
	global_load_dwordx4 v[108:111], v[30:31], off
	s_waitcnt vmcnt(19)
	ds_write_b128 v20, v[144:147]
	s_waitcnt vmcnt(18)
	ds_write_b128 v21, v[148:151]
	s_waitcnt vmcnt(17)
	ds_write_b128 v22, v[152:155]
	s_waitcnt vmcnt(16)
	ds_write_b128 v23, v[156:159]

; #define GLOAD(RA, RB, kt) { _Pragma("unroll") for (int i = 0; i < 8; ++i) { const int ia = (tail && i >= 4) ? i - 4 : i; \
;     RA[i] = *(const u32x4*)(abase + ((size_t)(32 * ia) * lda + (kt) * 64) * 2 + aoff); RB[i] = *(const u32x4*)(bbase + ((size_t)(32 * i) * K + (kt) * 64) * 2 + boff); } }
; #define LWRITE(RA, RB, buf) { char* as_ = lds + (buf) * 2 * G_TILE; char* bs_ = as_ + G_TILE; _Pragma("unroll") for (int i = 0; i < 8; ++i) { *(u32x4*)(as_ + (lrow + 32 * i) * GS_B + lch * 16) = RA[i]; *(u32x4*)(bs_ + (lrow + 32 * i) * GS_B + lch * 16) = RB[i]; } }
; template <int EPI>
; DEV void gemm_tile(CParams& p, int layer, const bf16_t* __restrict__ A, int lda, const bf16_t* __restrict__ Bt, int K, int m0, int n0, int nt, char* lds, const int swave) {
;     ...
;   const char* asr = lds + (wm * 128 + lr) * GS_B + hh * 16;
;   const char* bsr = lds + G_TILE + (wn * 128 + lr) * GS_B + hh * 16;
;   char* wsw = lds + lrow * GS_B + lch * 16;
;     ...
;   GLOAD(ra0, rb0, 0); GLOAD(ra1, rb1, 1); LWRITE(ra0, rb0, 0); __syncthreads();
; #pragma unroll 1
;   for (int kt = 0; kt < nk; kt += 2) {
;     if (kt + 2 < nk) GLOAD(ra0, rb0, kt + 2);
;     COMPUTE(0, ra1, rb1, 1, true);
;     __syncthreads();
;     const bool more = kt + 2 < nk;
;     if (kt + 3 < nk) GLOAD(ra1, rb1, kt + 3);
;     COMPUTE(1, ra0, rb0, 0, more);
;     __syncthreads();
.LBB0_179:
	v_add_u32_e32 v200, 0x1b000, v6
	v_add_u32_e32 v201, 0x12000, v26
	s_andn2_b64 vcc, exec, s[60:61]
	s_cbranch_vccnz .Lpg_i2_nomore
	ds_read_b128 v[164:167], v201
	ds_read_b128 v[168:171], v201 offset:4608
	ds_read_b128 v[172:175], v201 offset:9216
	ds_read_b128 v[176:179], v201 offset:13824
	ds_read_b128 v[160:163], v200
	ds_read_b128 v[180:183], v200 offset:4608
	s_waitcnt lgkmcnt(1)
	v_mfma_f32_32x32x16_bf16 a[96:111], v[160:163], v[164:167], a[96:111]
	v_mfma_f32_32x32x16_bf16 a[0:15], v[160:163], v[168:171], a[0:15]
	v_mfma_f32_32x32x16_bf16 a[16:31], v[160:163], v[172:175], a[16:31]
	v_mfma_f32_32x32x16_bf16 a[32:47], v[160:163], v[176:179], a[32:47]
	ds_read_b128 v[160:163], v200 offset:9216
	ds_read_b128 v[184:187], v201 offset:32
	ds_read_b128 v[188:191], v201 offset:4640
	s_lshl_b32 s34, s2, 7
	s_lshl_b32 s44, s2, 6
	v_lshl_add_u64 v[28:29], v[2:3], 0, s[34:35]
	v_lshl_add_u64 v[30:31], v[4:5], 0, s[34:35]
	s_add_i32 s2, s2, s28
	global_load_dwordx4 v[84:87], v[28:29], off
	s_waitcnt lgkmcnt(3)
	v_mfma_f32_32x32x16_bf16 a[80:95], v[180:183], v[164:167], a[80:95]
	v_mfma_f32_32x32x16_bf16 a[48:63], v[180:183], v[168:171], a[48:63]
	v_mfma_f32_32x32x16_bf16 a[64:79], v[180:183], v[172:175], a[64:79]
	v_mfma_f32_32x32x16_bf16 a[112:127], v[180:183], v[176:179], a[112:127]
	ds_read_b128 v[180:183], v200 offset:13824
	ds_read_b128 v[192:195], v201 offset:9248
	ds_read_b128 v[196:199], v201 offset:13856
	global_load_dwordx4 v[88:91], v[30:31], off
	s_waitcnt lgkmcnt(5)
	v_mfma_f32_32x32x16_bf16 a[128:143], v[160:163], v[164:167], a[128:143]
	v_mfma_f32_32x32x16_bf16 a[144:159], v[160:163], v[168:171], a[144:159]
	v_mfma_f32_32x32x16_bf16 a[160:175], v[160:163], v[172:175], a[160:175]
	v_mfma_f32_32x32x16_bf16 a[176:191], v[160:163], v[176:179], a[176:191]
	ds_read_b128 v[160:163], v200 offset:32
	v_lshl_add_u64 v[28:29], v[28:29], 0, s[8:9]
	v_lshl_add_u64 v[30:31], v[30:31], 0, s[8:9]
	s_lshl_b32 s2, s2, 7
	s_mov_b32 s3, s35
	global_load_dwordx4 v[96:99], v[28:29], off
	s_waitcnt lgkmcnt(3)
	v_mfma_f32_32x32x16_bf16 a[192:207], v[180:183], v[164:167], a[192:207]
	v_mfma_f32_32x32x16_bf16 a[208:223], v[180:183], v[168:171], a[208:223]
	v_mfma_f32_32x32x16_bf16 a[224:239], v[180:183], v[172:175], a[224:239]
	v_mfma_f32_32x32x16_bf16 a[240:255], v[180:183], v[176:179], a[240:255]
	ds_read_b128 v[180:183], v200 offset:4640
	global_load_dwordx4 v[104:107], v[30:31], off
	s_waitcnt vmcnt(19)
	ds_write_b128 v7, v[32:35]
	s_waitcnt vmcnt(18)
	ds_write_b128 v7, v[36:39] offset:36864
	s_waitcnt vmcnt(17)
	ds_write_b128 v7, v[40:43] offset:4608
	s_waitcnt vmcnt(16)
	ds_write_b128 v7, v[44:47] offset:41472
	s_waitcnt lgkmcnt(5)
	v_mfma_f32_32x32x16_bf16 a[96:111], v[160:163], v[184:187], a[96:111]
	v_mfma_f32_32x32x16_bf16 a[0:15], v[160:163], v[188:191], a[0:15]
	v_mfma_f32_32x32x16_bf16 a[16:31], v[160:163], v[192:195], a[16:31]
	v_mfma_f32_32x32x16_bf16 a[32:47], v[160:163], v[196:199], a[32:47]
	ds_read_b128 v[160:163], v200 offset:9248
	ds_read_b128 v[164:167], v201 offset:64
	ds_read_b128 v[168:171], v201 offset:4672
	v_lshl_add_u64 v[28:29], v[2:3], 0, s[2:3]
	v_lshl_add_u64 v[30:31], v[4:5], 0, s[2:3]
	s_add_i32 s2, s44, s38
	s_lshl_b32 s2, s2, 1
	global_load_dwordx4 v[112:115], v[28:29], off
	s_waitcnt lgkmcnt(7)
	v_mfma_f32_32x32x16_bf16 a[80:95], v[180:183], v[184:187], a[80:95]
	v_mfma_f32_32x32x16_bf16 a[48:63], v[180:183], v[188:191], a[48:63]
	v_mfma_f32_32x32x16_bf16 a[64:79], v[180:183], v[192:195], a[64:79]
	v_mfma_f32_32x32x16_bf16 a[112:127], v[180:183], v[196:199], a[112:127]
	ds_read_b128 v[180:183], v200 offset:13856
	ds_read_b128 v[172:175], v201 offset:9280
	ds_read_b128 v[176:179], v201 offset:13888
	global_load_dwordx4 v[116:119], v[30:31], off
	s_waitcnt lgkmcnt(5)
	v_mfma_f32_32x32x16_bf16 a[128:143], v[160:163], v[184:187], a[128:143]
	v_mfma_f32_32x32x16_bf16 a[144:159], v[160:163], v[188:191], a[144:159]
	v_mfma_f32_32x32x16_bf16 a[160:175], v[160:163], v[192:195], a[160:175]
	v_mfma_f32_32x32x16_bf16 a[176:191], v[160:163], v[196:199], a[176:191]
	ds_read_b128 v[160:163], v200 offset:64
	v_lshl_add_u64 v[28:29], v[2:3], 0, s[2:3]
	v_lshl_add_u64 v[30:31], v[4:5], 0, s[2:3]
	s_add_i32 s34, s34, s91
	s_add_i32 s2, s44, s39
	global_load_dwordx4 v[120:123], v[28:29], off
	s_waitcnt lgkmcnt(3)
	v_mfma_f32_32x32x16_bf16 a[192:207], v[180:183], v[184:187], a[192:207]
	v_mfma_f32_32x32x16_bf16 a[208:223], v[180:183], v[188:191], a[208:223]
	v_mfma_f32_32x32x16_bf16 a[224:239], v[180:183], v[192:195], a[224:239]
	v_mfma_f32_32x32x16_bf16 a[240:255], v[180:183], v[196:199], a[240:255]
	ds_read_b128 v[180:183], v200 offset:4672
	global_load_dwordx4 v[124:127], v[30:31], off
	s_waitcnt vmcnt(19)
; #define GLOAD(RA, RB, kt) { _Pragma("unroll") for (int i = 0; i < 8; ++i) { const int ia = (tail && i >= 4) ? i - 4 : i; \
;     RA[i] = *(const u32x4*)(abase + ((size_t)(32 * ia) * lda + (kt) * 64) * 2 + aoff); RB[i] = *(const u32x4*)(bbase + ((size_t)(32 * i) * K + (kt) * 64) * 2 + boff); } }
; #define LWRITE(RA, RB, buf) { char* as_ = lds + (buf) * 2 * G_TILE; char* bs_ = as_ + G_TILE; _Pragma("unroll") for (int i = 0; i < 8; ++i) { *(u32x4*)(as_ + (lrow + 32 * i) * GS_B + lch * 16) = RA[i]; *(u32x4*)(bs_ + (lrow + 32 * i) * GS_B + lch * 16) = RB[i]; } }
; template <int EPI>
; DEV void gemm_tile(CParams& p, int layer, const bf16_t* __restrict__ A, int lda, const bf16_t* __restrict__ Bt, int K, int m0, int n0, int nt, char* lds, const int swave) {
;     ...
;   GLOAD(ra0, rb0, 0); GLOAD(ra1, rb1, 1); LWRITE(ra0, rb0, 0); __syncthreads();
; #pragma unroll 1
;   for (int kt = 0; kt < nk; kt += 2) {
;     if (kt + 2 < nk) GLOAD(ra0, rb0, kt + 2);
;     COMPUTE(0, ra1, rb1, 1, true);
;     __syncthreads();
;     const bool more = kt + 2 < nk;
;     if (kt + 3 < nk) GLOAD(ra1, rb1, kt + 3);
;     COMPUTE(1, ra0, rb0, 0, more);
;     __syncthreads();
;   }
	ds_write_b128 v7, v[48:51] offset:9216
	s_waitcnt vmcnt(18)
	ds_write_b128 v7, v[52:55] offset:46080
	s_waitcnt vmcnt(17)
	ds_write_b128 v7, v[56:59] offset:13824
	s_waitcnt vmcnt(16)
	ds_write_b128 v7, v[60:63] offset:50688
	s_waitcnt lgkmcnt(5)
	v_mfma_f32_32x32x16_bf16 a[96:111], v[160:163], v[164:167], a[96:111]
	v_mfma_f32_32x32x16_bf16 a[0:15], v[160:163], v[168:171], a[0:15]
	v_mfma_f32_32x32x16_bf16 a[16:31], v[160:163], v[172:175], a[16:31]
	v_mfma_f32_32x32x16_bf16 a[32:47], v[160:163], v[176:179], a[32:47]
	ds_read_b128 v[160:163], v200 offset:9280
	ds_read_b128 v[184:187], v201 offset:96
	ds_read_b128 v[188:191], v201 offset:4704
	v_lshl_add_u64 v[28:29], v[2:3], 0, s[34:35]
	v_lshl_add_u64 v[30:31], v[4:5], 0, s[34:35]
	s_lshl_b32 s34, s2, 1
	s_add_i32 s2, s44, s68
	global_load_dwordx4 v[128:131], v[28:29], off
	s_waitcnt lgkmcnt(7)
	v_mfma_f32_32x32x16_bf16 a[80:95], v[180:183], v[164:167], a[80:95]
	v_mfma_f32_32x32x16_bf16 a[48:63], v[180:183], v[168:171], a[48:63]
	v_mfma_f32_32x32x16_bf16 a[64:79], v[180:183], v[172:175], a[64:79]
	v_mfma_f32_32x32x16_bf16 a[112:127], v[180:183], v[176:179], a[112:127]
	ds_read_b128 v[180:183], v200 offset:13888
	ds_read_b128 v[192:195], v201 offset:9312
	ds_read_b128 v[196:199], v201 offset:13920
	global_load_dwordx4 v[132:135], v[30:31], off
	s_waitcnt lgkmcnt(5)
	v_mfma_f32_32x32x16_bf16 a[128:143], v[160:163], v[164:167], a[128:143]
	v_mfma_f32_32x32x16_bf16 a[144:159], v[160:163], v[168:171], a[144:159]
	v_mfma_f32_32x32x16_bf16 a[160:175], v[160:163], v[172:175], a[160:175]
	v_mfma_f32_32x32x16_bf16 a[176:191], v[160:163], v[176:179], a[176:191]
	ds_read_b128 v[160:163], v200 offset:96
	v_lshl_add_u64 v[28:29], v[2:3], 0, s[34:35]
	v_lshl_add_u64 v[30:31], v[4:5], 0, s[34:35]
	s_lshl_b32 s34, s2, 1
	s_add_i32 s44, s44, s40
	global_load_dwordx4 v[136:139], v[28:29], off
	s_waitcnt lgkmcnt(3)
	v_mfma_f32_32x32x16_bf16 a[192:207], v[180:183], v[164:167], a[192:207]
	v_mfma_f32_32x32x16_bf16 a[208:223], v[180:183], v[168:171], a[208:223]
	v_mfma_f32_32x32x16_bf16 a[224:239], v[180:183], v[172:175], a[224:239]
	v_mfma_f32_32x32x16_bf16 a[240:255], v[180:183], v[176:179], a[240:255]
	ds_read_b128 v[180:183], v200 offset:4704
	global_load_dwordx4 v[140:143], v[30:31], off
	s_waitcnt vmcnt(19)
	ds_write_b128 v7, v[64:67] offset:18432
	s_waitcnt vmcnt(18)
	ds_write_b128 v7, v[68:71] offset:55296
	s_waitcnt vmcnt(17)
	ds_write_b128 v7, v[72:75] offset:23040
	s_waitcnt vmcnt(16)
	ds_write_b128 v7, v[76:79] offset:59904
	s_waitcnt lgkmcnt(5)
	v_mfma_f32_32x32x16_bf16 a[96:111], v[160:163], v[184:187], a[96:111]
	v_mfma_f32_32x32x16_bf16 a[0:15], v[160:163], v[188:191], a[0:15]
	v_mfma_f32_32x32x16_bf16 a[16:31], v[160:163], v[192:195], a[16:31]
	v_mfma_f32_32x32x16_bf16 a[32:47], v[160:163], v[196:199], a[32:47]
	ds_read_b128 v[160:163], v200 offset:9312
	v_lshl_add_u64 v[28:29], v[2:3], 0, s[34:35]
	v_lshl_add_u64 v[30:31], v[4:5], 0, s[34:35]
	s_lshl_b32 s34, s44, 1
	global_load_dwordx4 v[144:147], v[28:29], off
	s_waitcnt lgkmcnt(5)
	v_mfma_f32_32x32x16_bf16 a[80:95], v[180:183], v[184:187], a[80:95]
	v_mfma_f32_32x32x16_bf16 a[48:63], v[180:183], v[188:191], a[48:63]
	v_mfma_f32_32x32x16_bf16 a[64:79], v[180:183], v[192:195], a[64:79]
	v_mfma_f32_32x32x16_bf16 a[112:127], v[180:183], v[196:199], a[112:127]
	ds_read_b128 v[180:183], v200 offset:13920
	global_load_dwordx4 v[148:151], v[30:31], off
	s_waitcnt lgkmcnt(1)
	v_mfma_f32_32x32x16_bf16 a[128:143], v[160:163], v[184:187], a[128:143]
	v_mfma_f32_32x32x16_bf16 a[144:159], v[160:163], v[188:191], a[144:159]
	v_mfma_f32_32x32x16_bf16 a[160:175], v[160:163], v[192:195], a[160:175]
	v_mfma_f32_32x32x16_bf16 a[176:191], v[160:163], v[196:199], a[176:191]
	v_lshl_add_u64 v[28:29], v[2:3], 0, s[34:35]
	v_lshl_add_u64 v[30:31], v[4:5], 0, s[34:35]
	global_load_dwordx4 v[152:155], v[28:29], off
	s_waitcnt lgkmcnt(0)
	v_mfma_f32_32x32x16_bf16 a[192:207], v[180:183], v[184:187], a[192:207]
	v_mfma_f32_32x32x16_bf16 a[208:223], v[180:183], v[188:191], a[208:223]
	v_mfma_f32_32x32x16_bf16 a[224:239], v[180:183], v[192:195], a[224:239]
	v_mfma_f32_32x32x16_bf16 a[240:255], v[180:183], v[196:199], a[240:255]
	global_load_dwordx4 v[156:159], v[30:31], off
	s_waitcnt vmcnt(19)
	ds_write_b128 v7, v[80:83] offset:27648
	s_waitcnt vmcnt(18)
	ds_write_b128 v7, v[92:95] offset:64512
	s_waitcnt vmcnt(17)
	ds_write_b128 v7, v[100:103] offset:32256
	s_waitcnt vmcnt(16)
	ds_write_b128 v24, v[108:111]
	s_branch .LBB0_158

; #define GLOAD(RA, RB, kt) { _Pragma("unroll") for (int i = 0; i < 8; ++i) { const int ia = (tail && i >= 4) ? i - 4 : i; \
;     RA[i] = *(const u32x4*)(abase + ((size_t)(32 * ia) * lda + (kt) * 64) * 2 + aoff); RB[i] = *(const u32x4*)(bbase + ((size_t)(32 * i) * K + (kt) * 64) * 2 + boff); } }
; #define LWRITE(RA, RB, buf) { char* as_ = lds + (buf) * 2 * G_TILE; char* bs_ = as_ + G_TILE; _Pragma("unroll") for (int i = 0; i < 8; ++i) { *(u32x4*)(as_ + (lrow + 32 * i) * GS_B + lch * 16) = RA[i]; *(u32x4*)(bs_ + (lrow + 32 * i) * GS_B + lch * 16) = RB[i]; } }
; template <int EPI>
; DEV void gemm_tile(CParams& p, int layer, const bf16_t* __restrict__ A, int lda, const bf16_t* __restrict__ Bt, int K, int m0, int n0, int nt, char* lds, const int swave) {
;     ...
;   const char* asr = lds + (wm * 128 + lr) * GS_B + hh * 16;
;   const char* bsr = lds + G_TILE + (wn * 128 + lr) * GS_B + hh * 16;
;   char* wsw = lds + lrow * GS_B + lch * 16;
;     ...
;   GLOAD(ra0, rb0, 0); GLOAD(ra1, rb1, 1); LWRITE(ra0, rb0, 0); __syncthreads();
; #pragma unroll 1
;   for (int kt = 0; kt < nk; kt += 2) {
;     if (kt + 2 < nk) GLOAD(ra0, rb0, kt + 2);
;     COMPUTE(0, ra1, rb1, 1, true);
;     __syncthreads();
.LBB0_921:
	s_cmp_eq_u32 s42, 0
	s_cbranch_scc0 .Lzi_i3
	ds_read_b128 v[184:187], v45
	ds_read_b128 v[188:191], v45 offset:4608
	ds_read_b128 v[192:195], v45 offset:9216
	ds_read_b128 v[196:199], v45 offset:13824
	ds_read_b128 v[180:183], v49
	ds_read_b128 v[204:207], v49 offset:4608
	s_waitcnt lgkmcnt(1)
	v_mfma_f32_32x32x16_bf16 a[0:15], v[180:183], v[184:187], 0
	v_mfma_f32_32x32x16_bf16 a[16:31], v[180:183], v[188:191], 0
	v_mfma_f32_32x32x16_bf16 a[32:47], v[180:183], v[192:195], 0
	v_mfma_f32_32x32x16_bf16 a[48:63], v[180:183], v[196:199], 0
	ds_read_b128 v[180:183], v49 offset:9216
	ds_read_b128 v[208:211], v45 offset:32
	ds_read_b128 v[212:215], v45 offset:4640
	v_lshl_add_u64 v[50:51], v[0:1], 0, s[34:35]
	global_load_dwordx4 v[52:55], v[50:51], off
	s_waitcnt lgkmcnt(3)
	v_mfma_f32_32x32x16_bf16 a[64:79], v[204:207], v[184:187], 0
	v_mfma_f32_32x32x16_bf16 a[80:95], v[204:207], v[188:191], 0
	v_mfma_f32_32x32x16_bf16 a[96:111], v[204:207], v[192:195], 0
	v_mfma_f32_32x32x16_bf16 a[112:127], v[204:207], v[196:199], 0
	ds_read_b128 v[204:207], v49 offset:13824
	ds_read_b128 v[216:219], v45 offset:9248
	ds_read_b128 v[220:223], v45 offset:13856
	v_lshl_add_u64 v[50:51], v[2:3], 0, s[34:35]
	s_or_b32 s2, s34, 0x10000
	s_mov_b32 s3, s35
	global_load_dwordx4 v[56:59], v[50:51], off
	s_waitcnt lgkmcnt(5)
	v_mfma_f32_32x32x16_bf16 a[128:143], v[180:183], v[184:187], 0
	v_mfma_f32_32x32x16_bf16 a[144:159], v[180:183], v[188:191], 0
	v_mfma_f32_32x32x16_bf16 a[160:175], v[180:183], v[192:195], 0
	v_mfma_f32_32x32x16_bf16 a[176:191], v[180:183], v[196:199], 0
	ds_read_b128 v[180:183], v49 offset:32
	v_lshl_add_u64 v[50:51], v[0:1], 0, s[2:3]
	global_load_dwordx4 v[60:63], v[50:51], off
	s_waitcnt lgkmcnt(3)
	v_mfma_f32_32x32x16_bf16 a[192:207], v[204:207], v[184:187], 0
	v_mfma_f32_32x32x16_bf16 a[208:223], v[204:207], v[188:191], 0
	v_mfma_f32_32x32x16_bf16 a[224:239], v[204:207], v[192:195], 0
	v_mfma_f32_32x32x16_bf16 a[240:255], v[204:207], v[196:199], 0
	ds_read_b128 v[204:207], v49 offset:4640
	v_lshl_add_u64 v[50:51], v[2:3], 0, s[2:3]
	s_or_b32 s2, s34, 0x20000
	global_load_dwordx4 v[64:67], v[50:51], off
	s_waitcnt vmcnt(19)
	ds_write_b128 v31, v[104:107]
	s_waitcnt vmcnt(18)
	ds_write_b128 v32, v[108:111]
	s_waitcnt vmcnt(17)
	ds_write_b128 v41, v[96:99]
	s_waitcnt vmcnt(16)
	ds_write_b128 v42, v[100:103]
	s_waitcnt lgkmcnt(5)
	v_mfma_f32_32x32x16_bf16 a[0:15], v[180:183], v[208:211], a[0:15]
	v_mfma_f32_32x32x16_bf16 a[16:31], v[180:183], v[212:215], a[16:31]
	v_mfma_f32_32x32x16_bf16 a[32:47], v[180:183], v[216:219], a[32:47]
	v_mfma_f32_32x32x16_bf16 a[48:63], v[180:183], v[220:223], a[48:63]
	ds_read_b128 v[180:183], v49 offset:9248
	ds_read_b128 v[184:187], v45 offset:64
	ds_read_b128 v[188:191], v45 offset:4672
	v_lshl_add_u64 v[50:51], v[0:1], 0, s[2:3]
	global_load_dwordx4 v[68:71], v[50:51], off
	s_waitcnt lgkmcnt(7)
	v_mfma_f32_32x32x16_bf16 a[64:79], v[204:207], v[208:211], a[64:79]
	v_mfma_f32_32x32x16_bf16 a[80:95], v[204:207], v[212:215], a[80:95]
	v_mfma_f32_32x32x16_bf16 a[96:111], v[204:207], v[216:219], a[96:111]
	v_mfma_f32_32x32x16_bf16 a[112:127], v[204:207], v[220:223], a[112:127]
	ds_read_b128 v[204:207], v49 offset:13856
	ds_read_b128 v[192:195], v45 offset:9280
	ds_read_b128 v[196:199], v45 offset:13888
	v_lshl_add_u64 v[50:51], v[2:3], 0, s[2:3]
	s_or_b32 s2, s34, 0x30000
	global_load_dwordx4 v[72:75], v[50:51], off
	s_waitcnt lgkmcnt(5)
	v_mfma_f32_32x32x16_bf16 a[128:143], v[180:183], v[208:211], a[128:143]
	v_mfma_f32_32x32x16_bf16 a[144:159], v[180:183], v[212:215], a[144:159]
	v_mfma_f32_32x32x16_bf16 a[160:175], v[180:183], v[216:219], a[160:175]
	v_mfma_f32_32x32x16_bf16 a[176:191], v[180:183], v[220:223], a[176:191]
	ds_read_b128 v[180:183], v49 offset:64
	v_lshl_add_u64 v[50:51], v[0:1], 0, s[2:3]
	global_load_dwordx4 v[76:79], v[50:51], off
	s_waitcnt lgkmcnt(3)
	v_mfma_f32_32x32x16_bf16 a[192:207], v[204:207], v[208:211], a[192:207]
	v_mfma_f32_32x32x16_bf16 a[208:223], v[204:207], v[212:215], a[208:223]
	v_mfma_f32_32x32x16_bf16 a[224:239], v[204:207], v[216:219], a[224:239]
	v_mfma_f32_32x32x16_bf16 a[240:255], v[204:207], v[220:223], a[240:255]
	ds_read_b128 v[204:207], v49 offset:4672
	v_lshl_add_u64 v[50:51], v[2:3], 0, s[2:3]
	s_or_b32 s2, s34, 0x40000
	global_load_dwordx4 v[80:83], v[50:51], off
	s_waitcnt vmcnt(19)
	ds_write_b128 v37, v[116:119]
	s_waitcnt vmcnt(18)
	ds_write_b128 v38, v[120:123]
	s_waitcnt vmcnt(17)
	ds_write_b128 v39, v[128:131]
	s_waitcnt vmcnt(16)
	ds_write_b128 v40, v[132:135]
	s_waitcnt lgkmcnt(5)
	v_mfma_f32_32x32x16_bf16 a[0:15], v[180:183], v[184:187], a[0:15]
	v_mfma_f32_32x32x16_bf16 a[16:31], v[180:183], v[188:191], a[16:31]
	v_mfma_f32_32x32x16_bf16 a[32:47], v[180:183], v[192:195], a[32:47]
	v_mfma_f32_32x32x16_bf16 a[48:63], v[180:183], v[196:199], a[48:63]
	ds_read_b128 v[180:183], v49 offset:9280
	ds_read_b128 v[208:211], v45 offset:96
	ds_read_b128 v[212:215], v45 offset:4704
	v_lshl_add_u64 v[50:51], v[0:1], 0, s[2:3]
	global_load_dwordx4 v[84:87], v[50:51], off
	s_waitcnt lgkmcnt(7)
	v_mfma_f32_32x32x16_bf16 a[64:79], v[204:207], v[184:187], a[64:79]
	v_mfma_f32_32x32x16_bf16 a[80:95], v[204:207], v[188:191], a[80:95]
	v_mfma_f32_32x32x16_bf16 a[96:111], v[204:207], v[192:195], a[96:111]
	v_mfma_f32_32x32x16_bf16 a[112:127], v[204:207], v[196:199], a[112:127]
	ds_read_b128 v[204:207], v49 offset:13888
	ds_read_b128 v[216:219], v45 offset:9312
	ds_read_b128 v[220:223], v45 offset:13920
	v_lshl_add_u64 v[50:51], v[2:3], 0, s[2:3]
	s_or_b32 s2, s34, 0x50000
	global_load_dwordx4 v[88:91], v[50:51], off
	s_waitcnt lgkmcnt(5)
; #define GLOAD(RA, RB, kt) { _Pragma("unroll") for (int i = 0; i < 8; ++i) { const int ia = (tail && i >= 4) ? i - 4 : i; \
;     RA[i] = *(const u32x4*)(abase + ((size_t)(32 * ia) * lda + (kt) * 64) * 2 + aoff); RB[i] = *(const u32x4*)(bbase + ((size_t)(32 * i) * K + (kt) * 64) * 2 + boff); } }
; #define LWRITE(RA, RB, buf) { char* as_ = lds + (buf) * 2 * G_TILE; char* bs_ = as_ + G_TILE; _Pragma("unroll") for (int i = 0; i < 8; ++i) { *(u32x4*)(as_ + (lrow + 32 * i) * GS_B + lch * 16) = RA[i]; *(u32x4*)(bs_ + (lrow + 32 * i) * GS_B + lch * 16) = RB[i]; } }
; template <int EPI>
; DEV void gemm_tile(CParams& p, int layer, const bf16_t* __restrict__ A, int lda, const bf16_t* __restrict__ Bt, int K, int m0, int n0, int nt, char* lds, const int swave) {
;     ...
;   const char* asr = lds + (wm * 128 + lr) * GS_B + hh * 16;
;   const char* bsr = lds + G_TILE + (wn * 128 + lr) * GS_B + hh * 16;
;   char* wsw = lds + lrow * GS_B + lch * 16;
;     ...
;   GLOAD(ra0, rb0, 0); GLOAD(ra1, rb1, 1); LWRITE(ra0, rb0, 0); __syncthreads();
; #pragma unroll 1
;   for (int kt = 0; kt < nk; kt += 2) {
;     if (kt + 2 < nk) GLOAD(ra0, rb0, kt + 2);
;     COMPUTE(0, ra1, rb1, 1, true);
;     __syncthreads();
	v_mfma_f32_32x32x16_bf16 a[128:143], v[180:183], v[184:187], a[128:143]
	v_mfma_f32_32x32x16_bf16 a[144:159], v[180:183], v[188:191], a[144:159]
	v_mfma_f32_32x32x16_bf16 a[160:175], v[180:183], v[192:195], a[160:175]
	v_mfma_f32_32x32x16_bf16 a[176:191], v[180:183], v[196:199], a[176:191]
	ds_read_b128 v[180:183], v49 offset:96
	v_lshl_add_u64 v[50:51], v[0:1], 0, s[2:3]
	global_load_dwordx4 v[92:95], v[50:51], off
	s_waitcnt lgkmcnt(3)
	v_mfma_f32_32x32x16_bf16 a[192:207], v[204:207], v[184:187], a[192:207]
	v_mfma_f32_32x32x16_bf16 a[208:223], v[204:207], v[188:191], a[208:223]
	v_mfma_f32_32x32x16_bf16 a[224:239], v[204:207], v[192:195], a[224:239]
	v_mfma_f32_32x32x16_bf16 a[240:255], v[204:207], v[196:199], a[240:255]
	ds_read_b128 v[204:207], v49 offset:4704
	v_lshl_add_u64 v[50:51], v[2:3], 0, s[2:3]
	s_or_b32 s2, s34, 0x60000
	global_load_dwordx4 v[112:115], v[50:51], off
	s_waitcnt vmcnt(19)
	ds_write_b128 v33, v[136:139]
	s_waitcnt vmcnt(18)
	ds_write_b128 v34, v[144:147]
	s_waitcnt vmcnt(17)
	ds_write_b128 v35, v[148:151]
	s_waitcnt vmcnt(16)
	ds_write_b128 v36, v[156:159]
	s_waitcnt lgkmcnt(5)
	v_mfma_f32_32x32x16_bf16 a[0:15], v[180:183], v[208:211], a[0:15]
	v_mfma_f32_32x32x16_bf16 a[16:31], v[180:183], v[212:215], a[16:31]
	v_mfma_f32_32x32x16_bf16 a[32:47], v[180:183], v[216:219], a[32:47]
	v_mfma_f32_32x32x16_bf16 a[48:63], v[180:183], v[220:223], a[48:63]
	ds_read_b128 v[180:183], v49 offset:9312
	v_lshl_add_u64 v[50:51], v[0:1], 0, s[2:3]
	global_load_dwordx4 v[124:127], v[50:51], off
	s_waitcnt lgkmcnt(5)
	v_mfma_f32_32x32x16_bf16 a[64:79], v[204:207], v[208:211], a[64:79]
	v_mfma_f32_32x32x16_bf16 a[80:95], v[204:207], v[212:215], a[80:95]
	v_mfma_f32_32x32x16_bf16 a[96:111], v[204:207], v[216:219], a[96:111]
	v_mfma_f32_32x32x16_bf16 a[112:127], v[204:207], v[220:223], a[112:127]
	ds_read_b128 v[204:207], v49 offset:13920
	v_lshl_add_u64 v[50:51], v[2:3], 0, s[2:3]
	s_or_b32 s34, s34, 0x70000
	global_load_dwordx4 v[140:143], v[50:51], off
	s_waitcnt lgkmcnt(1)
	v_mfma_f32_32x32x16_bf16 a[128:143], v[180:183], v[208:211], a[128:143]
	v_mfma_f32_32x32x16_bf16 a[144:159], v[180:183], v[212:215], a[144:159]
	v_mfma_f32_32x32x16_bf16 a[160:175], v[180:183], v[216:219], a[160:175]
	v_mfma_f32_32x32x16_bf16 a[176:191], v[180:183], v[220:223], a[176:191]
	v_lshl_add_u64 v[50:51], v[0:1], 0, s[34:35]
	global_load_dwordx4 v[152:155], v[50:51], off
	s_waitcnt lgkmcnt(0)
	v_mfma_f32_32x32x16_bf16 a[192:207], v[204:207], v[208:211], a[192:207]
	v_mfma_f32_32x32x16_bf16 a[208:223], v[204:207], v[212:215], a[208:223]
	v_mfma_f32_32x32x16_bf16 a[224:239], v[204:207], v[216:219], a[224:239]
	v_mfma_f32_32x32x16_bf16 a[240:255], v[204:207], v[220:223], a[240:255]
	v_lshl_add_u64 v[50:51], v[2:3], 0, s[34:35]
	global_load_dwordx4 v[172:175], v[50:51], off
	s_waitcnt vmcnt(19)
	ds_write_b128 v43, v[160:163]
	s_waitcnt vmcnt(18)
	ds_write_b128 v44, v[164:167]
	s_waitcnt vmcnt(17)
	ds_write_b128 v46, v[168:171]
	s_waitcnt vmcnt(16)
	ds_write_b128 v47, v[176:179]
	s_branch .LBB0_937
.Lzi_i3:
	ds_read_b128 v[184:187], v45
	ds_read_b128 v[188:191], v45 offset:4608
	ds_read_b128 v[192:195], v45 offset:9216
	ds_read_b128 v[196:199], v45 offset:13824
	ds_read_b128 v[180:183], v49
	ds_read_b128 v[204:207], v49 offset:4608
	s_waitcnt lgkmcnt(1)
	v_mfma_f32_32x32x16_bf16 a[0:15], v[180:183], v[184:187], a[0:15]
	v_mfma_f32_32x32x16_bf16 a[16:31], v[180:183], v[188:191], a[16:31]
	v_mfma_f32_32x32x16_bf16 a[32:47], v[180:183], v[192:195], a[32:47]
	v_mfma_f32_32x32x16_bf16 a[48:63], v[180:183], v[196:199], a[48:63]
	ds_read_b128 v[180:183], v49 offset:9216
	ds_read_b128 v[208:211], v45 offset:32
	ds_read_b128 v[212:215], v45 offset:4640
	v_lshl_add_u64 v[50:51], v[0:1], 0, s[34:35]
	global_load_dwordx4 v[52:55], v[50:51], off
	s_waitcnt lgkmcnt(3)
	v_mfma_f32_32x32x16_bf16 a[64:79], v[204:207], v[184:187], a[64:79]
	v_mfma_f32_32x32x16_bf16 a[80:95], v[204:207], v[188:191], a[80:95]
	v_mfma_f32_32x32x16_bf16 a[96:111], v[204:207], v[192:195], a[96:111]
	v_mfma_f32_32x32x16_bf16 a[112:127], v[204:207], v[196:199], a[112:127]
	ds_read_b128 v[204:207], v49 offset:13824
	ds_read_b128 v[216:219], v45 offset:9248
	ds_read_b128 v[220:223], v45 offset:13856
	v_lshl_add_u64 v[50:51], v[2:3], 0, s[34:35]
	s_or_b32 s2, s34, 0x10000
	s_mov_b32 s3, s35
	global_load_dwordx4 v[56:59], v[50:51], off
	s_waitcnt lgkmcnt(5)
	v_mfma_f32_32x32x16_bf16 a[128:143], v[180:183], v[184:187], a[128:143]
	v_mfma_f32_32x32x16_bf16 a[144:159], v[180:183], v[188:191], a[144:159]
	v_mfma_f32_32x32x16_bf16 a[160:175], v[180:183], v[192:195], a[160:175]
	v_mfma_f32_32x32x16_bf16 a[176:191], v[180:183], v[196:199], a[176:191]
	ds_read_b128 v[180:183], v49 offset:32
	v_lshl_add_u64 v[50:51], v[0:1], 0, s[2:3]
	global_load_dwordx4 v[60:63], v[50:51], off
	s_waitcnt lgkmcnt(3)
	v_mfma_f32_32x32x16_bf16 a[192:207], v[204:207], v[184:187], a[192:207]
	v_mfma_f32_32x32x16_bf16 a[208:223], v[204:207], v[188:191], a[208:223]
	v_mfma_f32_32x32x16_bf16 a[224:239], v[204:207], v[192:195], a[224:239]
	v_mfma_f32_32x32x16_bf16 a[240:255], v[204:207], v[196:199], a[240:255]
	ds_read_b128 v[204:207], v49 offset:4640
	v_lshl_add_u64 v[50:51], v[2:3], 0, s[2:3]
	s_or_b32 s2, s34, 0x20000
	global_load_dwordx4 v[64:67], v[50:51], off
	s_waitcnt vmcnt(19)
	ds_write_b128 v31, v[104:107]
	s_waitcnt vmcnt(18)
	ds_write_b128 v32, v[108:111]
	s_waitcnt vmcnt(17)
	ds_write_b128 v41, v[96:99]
	s_waitcnt vmcnt(16)
	ds_write_b128 v42, v[100:103]
	s_waitcnt lgkmcnt(5)
; #define GLOAD(RA, RB, kt) { _Pragma("unroll") for (int i = 0; i < 8; ++i) { const int ia = (tail && i >= 4) ? i - 4 : i; \
;     RA[i] = *(const u32x4*)(abase + ((size_t)(32 * ia) * lda + (kt) * 64) * 2 + aoff); RB[i] = *(const u32x4*)(bbase + ((size_t)(32 * i) * K + (kt) * 64) * 2 + boff); } }
; #define LWRITE(RA, RB, buf) { char* as_ = lds + (buf) * 2 * G_TILE; char* bs_ = as_ + G_TILE; _Pragma("unroll") for (int i = 0; i < 8; ++i) { *(u32x4*)(as_ + (lrow + 32 * i) * GS_B + lch * 16) = RA[i]; *(u32x4*)(bs_ + (lrow + 32 * i) * GS_B + lch * 16) = RB[i]; } }
; template <int EPI>
; DEV void gemm_tile(CParams& p, int layer, const bf16_t* __restrict__ A, int lda, const bf16_t* __restrict__ Bt, int K, int m0, int n0, int nt, char* lds, const int swave) {
;     ...
;   GLOAD(ra0, rb0, 0); GLOAD(ra1, rb1, 1); LWRITE(ra0, rb0, 0); __syncthreads();
; #pragma unroll 1
;   for (int kt = 0; kt < nk; kt += 2) {
;     if (kt + 2 < nk) GLOAD(ra0, rb0, kt + 2);
;     COMPUTE(0, ra1, rb1, 1, true);
;     __syncthreads();
	v_mfma_f32_32x32x16_bf16 a[0:15], v[180:183], v[208:211], a[0:15]
	v_mfma_f32_32x32x16_bf16 a[16:31], v[180:183], v[212:215], a[16:31]
	v_mfma_f32_32x32x16_bf16 a[32:47], v[180:183], v[216:219], a[32:47]
	v_mfma_f32_32x32x16_bf16 a[48:63], v[180:183], v[220:223], a[48:63]
	ds_read_b128 v[180:183], v49 offset:9248
	ds_read_b128 v[184:187], v45 offset:64
	ds_read_b128 v[188:191], v45 offset:4672
	v_lshl_add_u64 v[50:51], v[0:1], 0, s[2:3]
	global_load_dwordx4 v[68:71], v[50:51], off
	s_waitcnt lgkmcnt(7)
	v_mfma_f32_32x32x16_bf16 a[64:79], v[204:207], v[208:211], a[64:79]
	v_mfma_f32_32x32x16_bf16 a[80:95], v[204:207], v[212:215], a[80:95]
	v_mfma_f32_32x32x16_bf16 a[96:111], v[204:207], v[216:219], a[96:111]
	v_mfma_f32_32x32x16_bf16 a[112:127], v[204:207], v[220:223], a[112:127]
	ds_read_b128 v[204:207], v49 offset:13856
	ds_read_b128 v[192:195], v45 offset:9280
	ds_read_b128 v[196:199], v45 offset:13888
	v_lshl_add_u64 v[50:51], v[2:3], 0, s[2:3]
	s_or_b32 s2, s34, 0x30000
	global_load_dwordx4 v[72:75], v[50:51], off
	s_waitcnt lgkmcnt(5)
	v_mfma_f32_32x32x16_bf16 a[128:143], v[180:183], v[208:211], a[128:143]
	v_mfma_f32_32x32x16_bf16 a[144:159], v[180:183], v[212:215], a[144:159]
	v_mfma_f32_32x32x16_bf16 a[160:175], v[180:183], v[216:219], a[160:175]
	v_mfma_f32_32x32x16_bf16 a[176:191], v[180:183], v[220:223], a[176:191]
	ds_read_b128 v[180:183], v49 offset:64
	v_lshl_add_u64 v[50:51], v[0:1], 0, s[2:3]
	global_load_dwordx4 v[76:79], v[50:51], off
	s_waitcnt lgkmcnt(3)
	v_mfma_f32_32x32x16_bf16 a[192:207], v[204:207], v[208:211], a[192:207]
	v_mfma_f32_32x32x16_bf16 a[208:223], v[204:207], v[212:215], a[208:223]
	v_mfma_f32_32x32x16_bf16 a[224:239], v[204:207], v[216:219], a[224:239]
	v_mfma_f32_32x32x16_bf16 a[240:255], v[204:207], v[220:223], a[240:255]
	ds_read_b128 v[204:207], v49 offset:4672
	v_lshl_add_u64 v[50:51], v[2:3], 0, s[2:3]
	s_or_b32 s2, s34, 0x40000
	global_load_dwordx4 v[80:83], v[50:51], off
	s_waitcnt vmcnt(19)
	ds_write_b128 v37, v[116:119]
	s_waitcnt vmcnt(18)
	ds_write_b128 v38, v[120:123]
	s_waitcnt vmcnt(17)
	ds_write_b128 v39, v[128:131]
	s_waitcnt vmcnt(16)
	ds_write_b128 v40, v[132:135]
	s_waitcnt lgkmcnt(5)
	v_mfma_f32_32x32x16_bf16 a[0:15], v[180:183], v[184:187], a[0:15]
	v_mfma_f32_32x32x16_bf16 a[16:31], v[180:183], v[188:191], a[16:31]
	v_mfma_f32_32x32x16_bf16 a[32:47], v[180:183], v[192:195], a[32:47]
	v_mfma_f32_32x32x16_bf16 a[48:63], v[180:183], v[196:199], a[48:63]
	ds_read_b128 v[180:183], v49 offset:9280
	ds_read_b128 v[208:211], v45 offset:96
	ds_read_b128 v[212:215], v45 offset:4704
	v_lshl_add_u64 v[50:51], v[0:1], 0, s[2:3]
	global_load_dwordx4 v[84:87], v[50:51], off
	s_waitcnt lgkmcnt(7)
	v_mfma_f32_32x32x16_bf16 a[64:79], v[204:207], v[184:187], a[64:79]
	v_mfma_f32_32x32x16_bf16 a[80:95], v[204:207], v[188:191], a[80:95]
	v_mfma_f32_32x32x16_bf16 a[96:111], v[204:207], v[192:195], a[96:111]
	v_mfma_f32_32x32x16_bf16 a[112:127], v[204:207], v[196:199], a[112:127]
	ds_read_b128 v[204:207], v49 offset:13888
	ds_read_b128 v[216:219], v45 offset:9312
	ds_read_b128 v[220:223], v45 offset:13920
	v_lshl_add_u64 v[50:51], v[2:3], 0, s[2:3]
	s_or_b32 s2, s34, 0x50000
	global_load_dwordx4 v[88:91], v[50:51], off
	s_waitcnt lgkmcnt(5)
	v_mfma_f32_32x32x16_bf16 a[128:143], v[180:183], v[184:187], a[128:143]
	v_mfma_f32_32x32x16_bf16 a[144:159], v[180:183], v[188:191], a[144:159]
	v_mfma_f32_32x32x16_bf16 a[160:175], v[180:183], v[192:195], a[160:175]
	v_mfma_f32_32x32x16_bf16 a[176:191], v[180:183], v[196:199], a[176:191]
	ds_read_b128 v[180:183], v49 offset:96
	v_lshl_add_u64 v[50:51], v[0:1], 0, s[2:3]
	global_load_dwordx4 v[92:95], v[50:51], off
	s_waitcnt lgkmcnt(3)
	v_mfma_f32_32x32x16_bf16 a[192:207], v[204:207], v[184:187], a[192:207]
	v_mfma_f32_32x32x16_bf16 a[208:223], v[204:207], v[188:191], a[208:223]
	v_mfma_f32_32x32x16_bf16 a[224:239], v[204:207], v[192:195], a[224:239]
	v_mfma_f32_32x32x16_bf16 a[240:255], v[204:207], v[196:199], a[240:255]
	ds_read_b128 v[204:207], v49 offset:4704
	v_lshl_add_u64 v[50:51], v[2:3], 0, s[2:3]
	s_or_b32 s2, s34, 0x60000
	global_load_dwordx4 v[112:115], v[50:51], off
	s_waitcnt vmcnt(19)
	ds_write_b128 v33, v[136:139]
	s_waitcnt vmcnt(18)
	ds_write_b128 v34, v[144:147]
	s_waitcnt vmcnt(17)
	ds_write_b128 v35, v[148:151]
	s_waitcnt vmcnt(16)
	ds_write_b128 v36, v[156:159]
	s_waitcnt lgkmcnt(5)
	v_mfma_f32_32x32x16_bf16 a[0:15], v[180:183], v[208:211], a[0:15]
	v_mfma_f32_32x32x16_bf16 a[16:31], v[180:183], v[212:215], a[16:31]
	v_mfma_f32_32x32x16_bf16 a[32:47], v[180:183], v[216:219], a[32:47]
	v_mfma_f32_32x32x16_bf16 a[48:63], v[180:183], v[220:223], a[48:63]
	ds_read_b128 v[180:183], v49 offset:9312
	v_lshl_add_u64 v[50:51], v[0:1], 0, s[2:3]
	global_load_dwordx4 v[124:127], v[50:51], off
	s_waitcnt lgkmcnt(5)
	v_mfma_f32_32x32x16_bf16 a[64:79], v[204:207], v[208:211], a[64:79]
	v_mfma_f32_32x32x16_bf16 a[80:95], v[204:207], v[212:215], a[80:95]
	v_mfma_f32_32x32x16_bf16 a[96:111], v[204:207], v[216:219], a[96:111]
	v_mfma_f32_32x32x16_bf16 a[112:127], v[204:207], v[220:223], a[112:127]
	ds_read_b128 v[204:207], v49 offset:13920
	v_lshl_add_u64 v[50:51], v[2:3], 0, s[2:3]
	s_or_b32 s34, s34, 0x70000
	global_load_dwordx4 v[140:143], v[50:51], off
	s_waitcnt lgkmcnt(1)
	v_mfma_f32_32x32x16_bf16 a[128:143], v[180:183], v[208:211], a[128:143]
	v_mfma_f32_32x32x16_bf16 a[144:159], v[180:183], v[212:215], a[144:159]
	v_mfma_f32_32x32x16_bf16 a[160:175], v[180:183], v[216:219], a[160:175]
	v_mfma_f32_32x32x16_bf16 a[176:191], v[180:183], v[220:223], a[176:191]
	v_lshl_add_u64 v[50:51], v[0:1], 0, s[34:35]
	global_load_dwordx4 v[152:155], v[50:51], off
	s_waitcnt lgkmcnt(0)
	v_mfma_f32_32x32x16_bf16 a[192:207], v[204:207], v[208:211], a[192:207]
	v_mfma_f32_32x32x16_bf16 a[208:223], v[204:207], v[212:215], a[208:223]
	v_mfma_f32_32x32x16_bf16 a[224:239], v[204:207], v[216:219], a[224:239]
	v_mfma_f32_32x32x16_bf16 a[240:255], v[204:207], v[220:223], a[240:255]
	v_lshl_add_u64 v[50:51], v[2:3], 0, s[34:35]
	global_load_dwordx4 v[172:175], v[50:51], off
	s_waitcnt vmcnt(19)
	ds_write_b128 v43, v[160:163]
	s_waitcnt vmcnt(18)
	ds_write_b128 v44, v[164:167]
	s_waitcnt vmcnt(17)
	ds_write_b128 v46, v[168:171]
	s_waitcnt vmcnt(16)
	ds_write_b128 v47, v[176:179]

; #define GLOAD(RA, RB, kt) { _Pragma("unroll") for (int i = 0; i < 8; ++i) { const int ia = (tail && i >= 4) ? i - 4 : i; \
;     RA[i] = *(const u32x4*)(abase + ((size_t)(32 * ia) * lda + (kt) * 64) * 2 + aoff); RB[i] = *(const u32x4*)(bbase + ((size_t)(32 * i) * K + (kt) * 64) * 2 + boff); } }
; #define LWRITE(RA, RB, buf) { char* as_ = lds + (buf) * 2 * G_TILE; char* bs_ = as_ + G_TILE; _Pragma("unroll") for (int i = 0; i < 8; ++i) { *(u32x4*)(as_ + (lrow + 32 * i) * GS_B + lch * 16) = RA[i]; *(u32x4*)(bs_ + (lrow + 32 * i) * GS_B + lch * 16) = RB[i]; } }
; template <int EPI>
; DEV void gemm_tile(CParams& p, int layer, const bf16_t* __restrict__ A, int lda, const bf16_t* __restrict__ Bt, int K, int m0, int n0, int nt, char* lds, const int swave) {
;     ...
;   const char* asr = lds + (wm * 128 + lr) * GS_B + hh * 16;
;   const char* bsr = lds + G_TILE + (wn * 128 + lr) * GS_B + hh * 16;
;   char* wsw = lds + lrow * GS_B + lch * 16;
;     ...
;   GLOAD(ra0, rb0, 0); GLOAD(ra1, rb1, 1); LWRITE(ra0, rb0, 0); __syncthreads();
; #pragma unroll 1
;   for (int kt = 0; kt < nk; kt += 2) {
;     if (kt + 2 < nk) GLOAD(ra0, rb0, kt + 2);
;     COMPUTE(0, ra1, rb1, 1, true);
;     __syncthreads();
;     const bool more = kt + 2 < nk;
;     if (kt + 3 < nk) GLOAD(ra1, rb1, kt + 3);
;     COMPUTE(1, ra0, rb0, 0, more);
;     __syncthreads();
.LBB0_939:
	v_add_u32_e32 v224, 0x1b000, v29
	v_add_u32_e32 v225, 0x12000, v45
	s_andn2_b64 vcc, exec, s[60:61]
	s_cbranch_vccnz .Lpg_i3_nomore
	ds_read_b128 v[184:187], v225
	ds_read_b128 v[188:191], v225 offset:4608
	ds_read_b128 v[192:195], v225 offset:9216
	ds_read_b128 v[196:199], v225 offset:13824
	ds_read_b128 v[180:183], v224
	ds_read_b128 v[204:207], v224 offset:4608
	s_waitcnt lgkmcnt(1)
	v_mfma_f32_32x32x16_bf16 a[0:15], v[180:183], v[184:187], a[0:15]
	v_mfma_f32_32x32x16_bf16 a[16:31], v[180:183], v[188:191], a[16:31]
	v_mfma_f32_32x32x16_bf16 a[32:47], v[180:183], v[192:195], a[32:47]
	v_mfma_f32_32x32x16_bf16 a[48:63], v[180:183], v[196:199], a[48:63]
	ds_read_b128 v[180:183], v224 offset:9216
	ds_read_b128 v[208:211], v225 offset:32
	ds_read_b128 v[212:215], v225 offset:4640
	s_lshl_b32 s34, s42, 7
	v_lshl_add_u64 v[50:51], v[0:1], 0, s[34:35]
	v_lshl_add_u64 v[96:97], v[2:3], 0, s[34:35]
	global_load_dwordx4 v[104:107], v[50:51], off offset:384
	s_waitcnt lgkmcnt(3)
	v_mfma_f32_32x32x16_bf16 a[64:79], v[204:207], v[184:187], a[64:79]
	v_mfma_f32_32x32x16_bf16 a[80:95], v[204:207], v[188:191], a[80:95]
	v_mfma_f32_32x32x16_bf16 a[96:111], v[204:207], v[192:195], a[96:111]
	v_mfma_f32_32x32x16_bf16 a[112:127], v[204:207], v[196:199], a[112:127]
	ds_read_b128 v[204:207], v224 offset:13824
	ds_read_b128 v[216:219], v225 offset:9248
	ds_read_b128 v[220:223], v225 offset:13856
	global_load_dwordx4 v[108:111], v[96:97], off offset:384
	s_waitcnt lgkmcnt(5)
	v_mfma_f32_32x32x16_bf16 a[128:143], v[180:183], v[184:187], a[128:143]
	v_mfma_f32_32x32x16_bf16 a[144:159], v[180:183], v[188:191], a[144:159]
	v_mfma_f32_32x32x16_bf16 a[160:175], v[180:183], v[192:195], a[160:175]
	v_mfma_f32_32x32x16_bf16 a[176:191], v[180:183], v[196:199], a[176:191]
	ds_read_b128 v[180:183], v224 offset:32
	v_add_co_u32_e32 v50, vcc, 0x10000, v50
	v_lshl_add_u64 v[120:121], v[6:7], 0, s[34:35]
	v_addc_co_u32_e32 v51, vcc, 0, v51, vcc
	v_add_co_u32_e32 v100, vcc, 0x10000, v96
	v_lshl_add_u64 v[132:133], v[10:11], 0, s[34:35]
	v_addc_co_u32_e32 v101, vcc, 0, v97, vcc
	global_load_dwordx4 v[96:99], v[50:51], off offset:384
	s_waitcnt lgkmcnt(3)
	v_mfma_f32_32x32x16_bf16 a[192:207], v[204:207], v[184:187], a[192:207]
	v_mfma_f32_32x32x16_bf16 a[208:223], v[204:207], v[188:191], a[208:223]
	v_mfma_f32_32x32x16_bf16 a[224:239], v[204:207], v[192:195], a[224:239]
	v_mfma_f32_32x32x16_bf16 a[240:255], v[204:207], v[196:199], a[240:255]
	ds_read_b128 v[204:207], v224 offset:4640
	s_nop 0
	global_load_dwordx4 v[100:103], v[100:101], off offset:384
	s_waitcnt vmcnt(19)
	ds_write_b128 v30, v[52:55]
	s_waitcnt vmcnt(18)
	ds_write_b128 v30, v[56:59] offset:36864
	s_waitcnt vmcnt(17)
	ds_write_b128 v30, v[60:63] offset:4608
	s_waitcnt vmcnt(16)
	ds_write_b128 v30, v[64:67] offset:41472
	s_waitcnt lgkmcnt(5)
	v_mfma_f32_32x32x16_bf16 a[0:15], v[180:183], v[208:211], a[0:15]
	v_mfma_f32_32x32x16_bf16 a[16:31], v[180:183], v[212:215], a[16:31]
	v_mfma_f32_32x32x16_bf16 a[32:47], v[180:183], v[216:219], a[32:47]
	v_mfma_f32_32x32x16_bf16 a[48:63], v[180:183], v[220:223], a[48:63]
	ds_read_b128 v[180:183], v224 offset:9248
	ds_read_b128 v[184:187], v225 offset:64
	ds_read_b128 v[188:191], v225 offset:4672
	v_lshl_add_u64 v[50:51], v[4:5], 0, s[34:35]
	global_load_dwordx4 v[116:119], v[50:51], off offset:384
	s_waitcnt lgkmcnt(7)
	v_mfma_f32_32x32x16_bf16 a[64:79], v[204:207], v[208:211], a[64:79]
	v_mfma_f32_32x32x16_bf16 a[80:95], v[204:207], v[212:215], a[80:95]
	v_mfma_f32_32x32x16_bf16 a[96:111], v[204:207], v[216:219], a[96:111]
	v_mfma_f32_32x32x16_bf16 a[112:127], v[204:207], v[220:223], a[112:127]
	ds_read_b128 v[204:207], v224 offset:13856
	ds_read_b128 v[192:195], v225 offset:9280
	ds_read_b128 v[196:199], v225 offset:13888
	s_nop 0
	global_load_dwordx4 v[120:123], v[120:121], off offset:384
	s_waitcnt lgkmcnt(5)
	v_mfma_f32_32x32x16_bf16 a[128:143], v[180:183], v[208:211], a[128:143]
	v_mfma_f32_32x32x16_bf16 a[144:159], v[180:183], v[212:215], a[144:159]
	v_mfma_f32_32x32x16_bf16 a[160:175], v[180:183], v[216:219], a[160:175]
	v_mfma_f32_32x32x16_bf16 a[176:191], v[180:183], v[220:223], a[176:191]
	ds_read_b128 v[180:183], v224 offset:64
	v_lshl_add_u64 v[50:51], v[8:9], 0, s[34:35]
	global_load_dwordx4 v[128:131], v[50:51], off offset:384
	s_waitcnt lgkmcnt(3)
	v_mfma_f32_32x32x16_bf16 a[192:207], v[204:207], v[208:211], a[192:207]
	v_mfma_f32_32x32x16_bf16 a[208:223], v[204:207], v[212:215], a[208:223]
	v_mfma_f32_32x32x16_bf16 a[224:239], v[204:207], v[216:219], a[224:239]
	v_mfma_f32_32x32x16_bf16 a[240:255], v[204:207], v[220:223], a[240:255]
	ds_read_b128 v[204:207], v224 offset:4672
	s_nop 0
	global_load_dwordx4 v[132:135], v[132:133], off offset:384
	s_waitcnt vmcnt(19)
; #define GLOAD(RA, RB, kt) { _Pragma("unroll") for (int i = 0; i < 8; ++i) { const int ia = (tail && i >= 4) ? i - 4 : i; \
;     RA[i] = *(const u32x4*)(abase + ((size_t)(32 * ia) * lda + (kt) * 64) * 2 + aoff); RB[i] = *(const u32x4*)(bbase + ((size_t)(32 * i) * K + (kt) * 64) * 2 + boff); } }
; #define LWRITE(RA, RB, buf) { char* as_ = lds + (buf) * 2 * G_TILE; char* bs_ = as_ + G_TILE; _Pragma("unroll") for (int i = 0; i < 8; ++i) { *(u32x4*)(as_ + (lrow + 32 * i) * GS_B + lch * 16) = RA[i]; *(u32x4*)(bs_ + (lrow + 32 * i) * GS_B + lch * 16) = RB[i]; } }
; template <int EPI>
; DEV void gemm_tile(CParams& p, int layer, const bf16_t* __restrict__ A, int lda, const bf16_t* __restrict__ Bt, int K, int m0, int n0, int nt, char* lds, const int swave) {
;     ...
;   GLOAD(ra0, rb0, 0); GLOAD(ra1, rb1, 1); LWRITE(ra0, rb0, 0); __syncthreads();
; #pragma unroll 1
;   for (int kt = 0; kt < nk; kt += 2) {
;     if (kt + 2 < nk) GLOAD(ra0, rb0, kt + 2);
;     COMPUTE(0, ra1, rb1, 1, true);
;     __syncthreads();
;     const bool more = kt + 2 < nk;
;     if (kt + 3 < nk) GLOAD(ra1, rb1, kt + 3);
;     COMPUTE(1, ra0, rb0, 0, more);
	ds_write_b128 v30, v[68:71] offset:9216
	s_waitcnt vmcnt(18)
	ds_write_b128 v30, v[72:75] offset:46080
	s_waitcnt vmcnt(17)
	ds_write_b128 v30, v[76:79] offset:13824
	s_waitcnt vmcnt(16)
	ds_write_b128 v30, v[80:83] offset:50688
	s_waitcnt lgkmcnt(5)
	v_mfma_f32_32x32x16_bf16 a[0:15], v[180:183], v[184:187], a[0:15]
	v_mfma_f32_32x32x16_bf16 a[16:31], v[180:183], v[188:191], a[16:31]
	v_mfma_f32_32x32x16_bf16 a[32:47], v[180:183], v[192:195], a[32:47]
	v_mfma_f32_32x32x16_bf16 a[48:63], v[180:183], v[196:199], a[48:63]
	ds_read_b128 v[180:183], v224 offset:9280
	ds_read_b128 v[208:211], v225 offset:96
	ds_read_b128 v[212:215], v225 offset:4704
	v_lshl_add_u64 v[50:51], v[12:13], 0, s[34:35]
	v_lshl_add_u64 v[144:145], v[14:15], 0, s[34:35]
	global_load_dwordx4 v[136:139], v[50:51], off offset:384
	s_waitcnt lgkmcnt(7)
	v_mfma_f32_32x32x16_bf16 a[64:79], v[204:207], v[184:187], a[64:79]
	v_mfma_f32_32x32x16_bf16 a[80:95], v[204:207], v[188:191], a[80:95]
	v_mfma_f32_32x32x16_bf16 a[96:111], v[204:207], v[192:195], a[96:111]
	v_mfma_f32_32x32x16_bf16 a[112:127], v[204:207], v[196:199], a[112:127]
	ds_read_b128 v[204:207], v224 offset:13888
	ds_read_b128 v[216:219], v225 offset:9312
	ds_read_b128 v[220:223], v225 offset:13920
	s_nop 0
	global_load_dwordx4 v[144:147], v[144:145], off offset:384
	s_waitcnt lgkmcnt(5)
	v_mfma_f32_32x32x16_bf16 a[128:143], v[180:183], v[184:187], a[128:143]
	v_mfma_f32_32x32x16_bf16 a[144:159], v[180:183], v[188:191], a[144:159]
	v_mfma_f32_32x32x16_bf16 a[160:175], v[180:183], v[192:195], a[160:175]
	v_mfma_f32_32x32x16_bf16 a[176:191], v[180:183], v[196:199], a[176:191]
	ds_read_b128 v[180:183], v224 offset:96
	v_lshl_add_u64 v[50:51], v[16:17], 0, s[34:35]
	v_lshl_add_u64 v[156:157], v[18:19], 0, s[34:35]
	global_load_dwordx4 v[148:151], v[50:51], off offset:384
	s_waitcnt lgkmcnt(3)
	v_mfma_f32_32x32x16_bf16 a[192:207], v[204:207], v[184:187], a[192:207]
	v_mfma_f32_32x32x16_bf16 a[208:223], v[204:207], v[188:191], a[208:223]
	v_mfma_f32_32x32x16_bf16 a[224:239], v[204:207], v[192:195], a[224:239]
	v_mfma_f32_32x32x16_bf16 a[240:255], v[204:207], v[196:199], a[240:255]
	ds_read_b128 v[204:207], v224 offset:4704
	s_nop 0
	global_load_dwordx4 v[156:159], v[156:157], off offset:384
	s_waitcnt vmcnt(19)
	ds_write_b128 v30, v[84:87] offset:18432
	s_waitcnt vmcnt(18)
	ds_write_b128 v30, v[88:91] offset:55296
	s_waitcnt vmcnt(17)
	ds_write_b128 v30, v[92:95] offset:23040
	s_waitcnt vmcnt(16)
	ds_write_b128 v30, v[112:115] offset:59904
	s_waitcnt lgkmcnt(5)
	v_mfma_f32_32x32x16_bf16 a[0:15], v[180:183], v[208:211], a[0:15]
	v_mfma_f32_32x32x16_bf16 a[16:31], v[180:183], v[212:215], a[16:31]
	v_mfma_f32_32x32x16_bf16 a[32:47], v[180:183], v[216:219], a[32:47]
	v_mfma_f32_32x32x16_bf16 a[48:63], v[180:183], v[220:223], a[48:63]
	ds_read_b128 v[180:183], v224 offset:9312
	v_lshl_add_u64 v[50:51], v[20:21], 0, s[34:35]
	v_lshl_add_u64 v[164:165], v[22:23], 0, s[34:35]
	global_load_dwordx4 v[160:163], v[50:51], off offset:384
	s_waitcnt lgkmcnt(5)
	v_mfma_f32_32x32x16_bf16 a[64:79], v[204:207], v[208:211], a[64:79]
	v_mfma_f32_32x32x16_bf16 a[80:95], v[204:207], v[212:215], a[80:95]
	v_mfma_f32_32x32x16_bf16 a[96:111], v[204:207], v[216:219], a[96:111]
	v_mfma_f32_32x32x16_bf16 a[112:127], v[204:207], v[220:223], a[112:127]
	ds_read_b128 v[204:207], v224 offset:13920
	s_nop 0
	global_load_dwordx4 v[164:167], v[164:165], off offset:384
	s_waitcnt lgkmcnt(1)
	v_mfma_f32_32x32x16_bf16 a[128:143], v[180:183], v[208:211], a[128:143]
	v_mfma_f32_32x32x16_bf16 a[144:159], v[180:183], v[212:215], a[144:159]
	v_mfma_f32_32x32x16_bf16 a[160:175], v[180:183], v[216:219], a[160:175]
	v_mfma_f32_32x32x16_bf16 a[176:191], v[180:183], v[220:223], a[176:191]
	v_lshl_add_u64 v[50:51], v[24:25], 0, s[34:35]
	v_lshl_add_u64 v[176:177], v[26:27], 0, s[34:35]
	global_load_dwordx4 v[168:171], v[50:51], off offset:384
	s_waitcnt lgkmcnt(0)
	v_mfma_f32_32x32x16_bf16 a[192:207], v[204:207], v[208:211], a[192:207]
	v_mfma_f32_32x32x16_bf16 a[208:223], v[204:207], v[212:215], a[208:223]
	v_mfma_f32_32x32x16_bf16 a[224:239], v[204:207], v[216:219], a[224:239]
	v_mfma_f32_32x32x16_bf16 a[240:255], v[204:207], v[220:223], a[240:255]
	s_nop 0
	global_load_dwordx4 v[176:179], v[176:177], off offset:384
	s_waitcnt vmcnt(19)
	ds_write_b128 v30, v[124:127] offset:27648
	s_waitcnt vmcnt(18)
	ds_write_b128 v30, v[140:143] offset:64512
	s_waitcnt vmcnt(17)
	ds_write_b128 v30, v[152:155] offset:32256
	s_waitcnt vmcnt(16)
	ds_write_b128 v48, v[172:175]
	s_branch .LBB0_918
